# gemm_in gate-sigmoid epilogue path rewritten by hand with packed f32 ops, in-place sigmoid chains, no hazard nops
# speedup vs baseline: 1.0925x; 1.0023x over previous
; __device__ __forceinline__ float sigmoidf_(float x) { return 1.0f / (1.0f + __builtin_amdgcn_exp2f(-1.4426950408889634f * x)); }
; #define EPIIN_PACK(w, a, b) do { (w).x = cvt_pk_bf16((a)[0], (a)[1]); (w).y = cvt_pk_bf16((a)[2], (a)[3]); (w).z = cvt_pk_bf16((b)[0], (b)[1]); (w).w = cvt_pk_bf16((b)[2], (b)[3]); } while (0)
;     __device__ __forceinline__ void operator()(const f32x4 (&acc_)[2][2][4][2], const Unit& u, int wr, int wc, int fr, int fq) const {
;     ...
;         const int pn = u.pn; const size_t rowb = (size_t)u.pm * BM + wr * 64 + fr;
;         f32x4 bv[2][2]; float r8[2][4];
;         { const float* bwp = bw + (size_t)(u.pm >> 4) * 4096 + pn * BM + wc * 32 + fq * 8;
; #pragma unroll
;           for (int bj = 0; bj < 2; ++bj)
; #pragma unroll
;               for (int n = 0; n < 2; ++n) bv[bj][n] = *(const f32x4*)(bwp + bj * HALF + n * 4);
; #pragma unroll
;           for (int ai = 0; ai < 2; ++ai)
; #pragma unroll
;               for (int m = 0; m < 4; ++m) r8[ai][m] = __builtin_amdgcn_rsqf(ssq1[rowb + ai * HALF + m * 16] * (1.0f / 1024.0f) + RMS_EPS); }
;     ...
; #pragma unroll
;             for (int ai = 0; ai < 2; ++ai)
; #pragma unroll
;                 for (int m = 0; m < 4; ++m) { const size_t row = rowb + ai * HALF + m * 16;
; #pragma unroll
;                     for (int bj = 0; bj < 2; ++bj) { f32x4 a = EPIIN_VAL(ai, bj, m, 0), b = EPIIN_VAL(ai, bj, m, 1);
; #pragma unroll
;                         for (int i = 0; i < 4; ++i) { a[i] = sigmoidf_(a[i]); b[i] = sigmoidf_(b[i]); }
;                         u32x4 w; EPIIN_PACK(w, a, b);
;                         *(u32x4*)(GATES + row * 2048 + (pn - 8) * 256 + bj * HALF + wc * 32 + fq * 8) = w; } }
.LBB0_555:
	s_ashr_i32 s6, s2, 4
	s_ashr_i32 s7, s6, 31
	s_ashr_i32 s3, s2, 31
	s_lshl_b64 s[6:7], s[6:7], 14
	s_add_u32 s30, s12, s6
	s_addc_u32 s34, s13, s7
	s_lshl_b32 s68, s46, 8
	s_ashr_i32 s69, s68, 31
	s_lshl_b64 s[6:7], s[68:69], 2
	s_add_u32 s6, s30, s6
	s_addc_u32 s7, s34, s7
	s_lshl_b32 s30, s50, 2
	s_add_u32 s6, s6, s30
	s_addc_u32 s7, s7, 0
	s_lshl_b64 s[2:3], s[2:3], 8
	s_add_u32 s42, s2, s49
	v_mov_b32_e32 v0, v221
	s_addc_u32 s43, s3, s95
	v_mov_b32_e32 v159, s43
	v_bfe_u32 v165, v0, 4, 2
	v_and_or_b32 v158, v0, 15, s42
	v_lshlrev_b32_e32 v94, 5, v165
	v_lshl_add_u64 v[176:177], v[158:159], 2, s[16:17]
	global_load_dwordx4 v[106:109], v94, s[6:7] offset:16
	global_load_dwordx4 v[110:113], v94, s[6:7]
	global_load_dwordx4 v[90:93], v94, s[6:7] offset:528
	s_nop 0
	global_load_dwordx4 v[94:97], v94, s[6:7] offset:512
	v_lshlrev_b32_e32 v167, 3, v165
	global_load_dword v174, v[176:177], off
	global_load_dword v172, v[176:177], off offset:64
	global_load_dword v170, v[176:177], off offset:128
	global_load_dword v168, v[176:177], off offset:192
	global_load_dword v166, v[176:177], off offset:512
	global_load_dword v164, v[176:177], off offset:576
	global_load_dword v162, v[176:177], off offset:640
	global_load_dword v160, v[176:177], off offset:704
	s_mov_b64 s[2:3], -1
	s_cmp_gt_i32 s46, 1
	s_waitcnt vmcnt(0)
	v_fmamk_f32 v174, v174, 0x3a800000, v231
	v_fmamk_f32 v172, v172, 0x3a800000, v231
	v_fmamk_f32 v170, v170, 0x3a800000, v231
	v_fmamk_f32 v168, v168, 0x3a800000, v231
	v_fmamk_f32 v166, v166, 0x3a800000, v231
	v_fmamk_f32 v164, v164, 0x3a800000, v231
	v_fmamk_f32 v162, v162, 0x3a800000, v231
	v_fmamk_f32 v160, v160, 0x3a800000, v231
	v_rsq_f32_e32 v174, v174
	v_rsq_f32_e32 v172, v172
	v_rsq_f32_e32 v170, v170
	v_rsq_f32_e32 v168, v168
	v_rsq_f32_e32 v166, v166
	v_rsq_f32_e32 v164, v164
	v_rsq_f32_e32 v162, v162
	v_rsq_f32_e32 v160, v160
	s_nop 0
	s_cbranch_scc0 .LBB0_565
	s_cmp_gt_u32 s46, 5
	s_cbranch_scc0 .LBB0_562
	s_cmp_lt_u32 s46, 8
	s_cbranch_scc1 .LBB0_559
	s_mov_b32 s100, 0xbfb8aa3b
	s_mov_b32 s101, 0xbfb8aa3b
	v_readlane_b32 s2, v255, 47
	v_readlane_b32 s3, v255, 48
	s_add_i32 s30, s68, 0xfffff800
	s_add_i32 s30, s30, s50
	s_lshl_b32 s30, s30, 1
	v_lshlrev_b32_e32 v242, 12, v158
	v_lshl_add_u32 v243, v167, 1, s30
	v_add_u32_e32 v242, v242, v243
	v_pk_fma_f32 v[142:143], v[142:143], v[174:175], v[110:111] op_sel_hi:[1,0,1]
	v_pk_fma_f32 v[144:145], v[144:145], v[174:175], v[112:113] op_sel_hi:[1,0,1]
	v_pk_fma_f32 v[138:139], v[138:139], v[174:175], v[106:107] op_sel_hi:[1,0,1]
	v_pk_fma_f32 v[140:141], v[140:141], v[174:175], v[108:109] op_sel_hi:[1,0,1]
	v_pk_fma_f32 v[134:135], v[134:135], v[174:175], v[94:95] op_sel_hi:[1,0,1]
	v_pk_fma_f32 v[136:137], v[136:137], v[174:175], v[96:97] op_sel_hi:[1,0,1]
	v_pk_fma_f32 v[130:131], v[130:131], v[174:175], v[90:91] op_sel_hi:[1,0,1]
	v_pk_fma_f32 v[132:133], v[132:133], v[174:175], v[92:93] op_sel_hi:[1,0,1]
	v_pk_mul_f32 v[142:143], v[142:143], s[100:101]
	v_pk_mul_f32 v[144:145], v[144:145], s[100:101]
	v_pk_mul_f32 v[138:139], v[138:139], s[100:101]
	v_pk_mul_f32 v[140:141], v[140:141], s[100:101]
	v_pk_mul_f32 v[134:135], v[134:135], s[100:101]
	v_pk_mul_f32 v[136:137], v[136:137], s[100:101]
	v_pk_mul_f32 v[130:131], v[130:131], s[100:101]
	v_pk_mul_f32 v[132:133], v[132:133], s[100:101]
	v_exp_f32_e32 v142, v142
	v_exp_f32_e32 v143, v143
	v_exp_f32_e32 v144, v144
	v_exp_f32_e32 v145, v145
	v_exp_f32_e32 v138, v138
	v_exp_f32_e32 v139, v139
	v_exp_f32_e32 v140, v140
	v_exp_f32_e32 v141, v141
	v_exp_f32_e32 v134, v134
	v_exp_f32_e32 v135, v135
	v_exp_f32_e32 v136, v136
	v_exp_f32_e32 v137, v137
	v_exp_f32_e32 v130, v130
	v_exp_f32_e32 v131, v131
	v_exp_f32_e32 v132, v132
	v_exp_f32_e32 v133, v133
	v_pk_add_f32 v[142:143], v[142:143], 1.0 op_sel_hi:[1,0]
	v_pk_add_f32 v[144:145], v[144:145], 1.0 op_sel_hi:[1,0]
	v_pk_add_f32 v[138:139], v[138:139], 1.0 op_sel_hi:[1,0]
	v_pk_add_f32 v[140:141], v[140:141], 1.0 op_sel_hi:[1,0]
	v_pk_add_f32 v[134:135], v[134:135], 1.0 op_sel_hi:[1,0]
	v_pk_add_f32 v[136:137], v[136:137], 1.0 op_sel_hi:[1,0]
	v_pk_add_f32 v[130:131], v[130:131], 1.0 op_sel_hi:[1,0]
	v_pk_add_f32 v[132:133], v[132:133], 1.0 op_sel_hi:[1,0]
	v_rcp_f32_e32 v142, v142
	v_rcp_f32_e32 v143, v143
	v_rcp_f32_e32 v144, v144
	v_rcp_f32_e32 v145, v145
	v_rcp_f32_e32 v138, v138
	v_rcp_f32_e32 v139, v139
	v_rcp_f32_e32 v140, v140
	v_rcp_f32_e32 v141, v141
	v_rcp_f32_e32 v134, v134
	v_rcp_f32_e32 v135, v135
	v_rcp_f32_e32 v136, v136
	v_rcp_f32_e32 v137, v137
	v_rcp_f32_e32 v130, v130
	v_rcp_f32_e32 v131, v131
	v_rcp_f32_e32 v132, v132
	v_rcp_f32_e32 v133, v133
	v_cvt_pk_bf16_f32 v244, v142, v143
	v_cvt_pk_bf16_f32 v245, v144, v145
	v_cvt_pk_bf16_f32 v246, v138, v139
	v_cvt_pk_bf16_f32 v247, v140, v141
	global_store_dwordx4 v242, v[244:247], s[2:3]
	v_cvt_pk_bf16_f32 v248, v134, v135
	v_cvt_pk_bf16_f32 v249, v136, v137
	v_cvt_pk_bf16_f32 v250, v130, v131
	v_cvt_pk_bf16_f32 v251, v132, v133
	global_store_dwordx4 v242, v[248:251], s[2:3] offset:256
	v_add_u32_e32 v242, 0x10000, v242
	v_pk_fma_f32 v[126:127], v[126:127], v[172:173], v[110:111] op_sel_hi:[1,0,1]
	v_pk_fma_f32 v[128:129], v[128:129], v[172:173], v[112:113] op_sel_hi:[1,0,1]
	v_pk_fma_f32 v[122:123], v[122:123], v[172:173], v[106:107] op_sel_hi:[1,0,1]
	v_pk_fma_f32 v[124:125], v[124:125], v[172:173], v[108:109] op_sel_hi:[1,0,1]
	v_pk_fma_f32 v[118:119], v[118:119], v[172:173], v[94:95] op_sel_hi:[1,0,1]
	v_pk_fma_f32 v[120:121], v[120:121], v[172:173], v[96:97] op_sel_hi:[1,0,1]
	v_pk_fma_f32 v[114:115], v[114:115], v[172:173], v[90:91] op_sel_hi:[1,0,1]
	v_pk_fma_f32 v[116:117], v[116:117], v[172:173], v[92:93] op_sel_hi:[1,0,1]
; __device__ __forceinline__ float sigmoidf_(float x) { return 1.0f / (1.0f + __builtin_amdgcn_exp2f(-1.4426950408889634f * x)); }
; #define EPIIN_PACK(w, a, b) do { (w).x = cvt_pk_bf16((a)[0], (a)[1]); (w).y = cvt_pk_bf16((a)[2], (a)[3]); (w).z = cvt_pk_bf16((b)[0], (b)[1]); (w).w = cvt_pk_bf16((b)[2], (b)[3]); } while (0)
;     __device__ __forceinline__ void operator()(const f32x4 (&acc_)[2][2][4][2], const Unit& u, int wr, int wc, int fr, int fq) const {
;     ...
; #pragma unroll
;             for (int ai = 0; ai < 2; ++ai)
; #pragma unroll
;                 for (int m = 0; m < 4; ++m) { const size_t row = rowb + ai * HALF + m * 16;
; #pragma unroll
;                     for (int bj = 0; bj < 2; ++bj) { f32x4 a = EPIIN_VAL(ai, bj, m, 0), b = EPIIN_VAL(ai, bj, m, 1);
; #pragma unroll
;                         for (int i = 0; i < 4; ++i) { a[i] = sigmoidf_(a[i]); b[i] = sigmoidf_(b[i]); }
;                         u32x4 w; EPIIN_PACK(w, a, b);
;                         *(u32x4*)(GATES + row * 2048 + (pn - 8) * 256 + bj * HALF + wc * 32 + fq * 8) = w; } }
	v_pk_mul_f32 v[126:127], v[126:127], s[100:101]
	v_pk_mul_f32 v[128:129], v[128:129], s[100:101]
	v_pk_mul_f32 v[122:123], v[122:123], s[100:101]
	v_pk_mul_f32 v[124:125], v[124:125], s[100:101]
	v_pk_mul_f32 v[118:119], v[118:119], s[100:101]
	v_pk_mul_f32 v[120:121], v[120:121], s[100:101]
	v_pk_mul_f32 v[114:115], v[114:115], s[100:101]
	v_pk_mul_f32 v[116:117], v[116:117], s[100:101]
	v_exp_f32_e32 v126, v126
	v_exp_f32_e32 v127, v127
	v_exp_f32_e32 v128, v128
	v_exp_f32_e32 v129, v129
	v_exp_f32_e32 v122, v122
	v_exp_f32_e32 v123, v123
	v_exp_f32_e32 v124, v124
	v_exp_f32_e32 v125, v125
	v_exp_f32_e32 v118, v118
	v_exp_f32_e32 v119, v119
	v_exp_f32_e32 v120, v120
	v_exp_f32_e32 v121, v121
	v_exp_f32_e32 v114, v114
	v_exp_f32_e32 v115, v115
	v_exp_f32_e32 v116, v116
	v_exp_f32_e32 v117, v117
	v_pk_add_f32 v[126:127], v[126:127], 1.0 op_sel_hi:[1,0]
	v_pk_add_f32 v[128:129], v[128:129], 1.0 op_sel_hi:[1,0]
	v_pk_add_f32 v[122:123], v[122:123], 1.0 op_sel_hi:[1,0]
	v_pk_add_f32 v[124:125], v[124:125], 1.0 op_sel_hi:[1,0]
	v_pk_add_f32 v[118:119], v[118:119], 1.0 op_sel_hi:[1,0]
	v_pk_add_f32 v[120:121], v[120:121], 1.0 op_sel_hi:[1,0]
	v_pk_add_f32 v[114:115], v[114:115], 1.0 op_sel_hi:[1,0]
	v_pk_add_f32 v[116:117], v[116:117], 1.0 op_sel_hi:[1,0]
	v_rcp_f32_e32 v126, v126
	v_rcp_f32_e32 v127, v127
	v_rcp_f32_e32 v128, v128
	v_rcp_f32_e32 v129, v129
	v_rcp_f32_e32 v122, v122
	v_rcp_f32_e32 v123, v123
	v_rcp_f32_e32 v124, v124
	v_rcp_f32_e32 v125, v125
	v_rcp_f32_e32 v118, v118
	v_rcp_f32_e32 v119, v119
	v_rcp_f32_e32 v120, v120
	v_rcp_f32_e32 v121, v121
	v_rcp_f32_e32 v114, v114
	v_rcp_f32_e32 v115, v115
	v_rcp_f32_e32 v116, v116
	v_rcp_f32_e32 v117, v117
	v_cvt_pk_bf16_f32 v244, v126, v127
	v_cvt_pk_bf16_f32 v245, v128, v129
	v_cvt_pk_bf16_f32 v246, v122, v123
	v_cvt_pk_bf16_f32 v247, v124, v125
	global_store_dwordx4 v242, v[244:247], s[2:3]
	v_cvt_pk_bf16_f32 v248, v118, v119
	v_cvt_pk_bf16_f32 v249, v120, v121
	v_cvt_pk_bf16_f32 v250, v114, v115
	v_cvt_pk_bf16_f32 v251, v116, v117
	global_store_dwordx4 v242, v[248:251], s[2:3] offset:256
	v_add_u32_e32 v242, 0x10000, v242
	v_pk_fma_f32 v[102:103], v[102:103], v[170:171], v[110:111] op_sel_hi:[1,0,1]
	v_pk_fma_f32 v[104:105], v[104:105], v[170:171], v[112:113] op_sel_hi:[1,0,1]
	v_pk_fma_f32 v[98:99], v[98:99], v[170:171], v[106:107] op_sel_hi:[1,0,1]
	v_pk_fma_f32 v[100:101], v[100:101], v[170:171], v[108:109] op_sel_hi:[1,0,1]
	v_pk_fma_f32 v[86:87], v[86:87], v[170:171], v[94:95] op_sel_hi:[1,0,1]
	v_pk_fma_f32 v[88:89], v[88:89], v[170:171], v[96:97] op_sel_hi:[1,0,1]
	v_pk_fma_f32 v[82:83], v[82:83], v[170:171], v[90:91] op_sel_hi:[1,0,1]
	v_pk_fma_f32 v[84:85], v[84:85], v[170:171], v[92:93] op_sel_hi:[1,0,1]
	v_pk_mul_f32 v[102:103], v[102:103], s[100:101]
	v_pk_mul_f32 v[104:105], v[104:105], s[100:101]
	v_pk_mul_f32 v[98:99], v[98:99], s[100:101]
	v_pk_mul_f32 v[100:101], v[100:101], s[100:101]
	v_pk_mul_f32 v[86:87], v[86:87], s[100:101]
	v_pk_mul_f32 v[88:89], v[88:89], s[100:101]
	v_pk_mul_f32 v[82:83], v[82:83], s[100:101]
	v_pk_mul_f32 v[84:85], v[84:85], s[100:101]
	v_exp_f32_e32 v102, v102
	v_exp_f32_e32 v103, v103
	v_exp_f32_e32 v104, v104
	v_exp_f32_e32 v105, v105
	v_exp_f32_e32 v98, v98
	v_exp_f32_e32 v99, v99
	v_exp_f32_e32 v100, v100
	v_exp_f32_e32 v101, v101
	v_exp_f32_e32 v86, v86
	v_exp_f32_e32 v87, v87
	v_exp_f32_e32 v88, v88
	v_exp_f32_e32 v89, v89
	v_exp_f32_e32 v82, v82
	v_exp_f32_e32 v83, v83
	v_exp_f32_e32 v84, v84
	v_exp_f32_e32 v85, v85
	v_pk_add_f32 v[102:103], v[102:103], 1.0 op_sel_hi:[1,0]
	v_pk_add_f32 v[104:105], v[104:105], 1.0 op_sel_hi:[1,0]
	v_pk_add_f32 v[98:99], v[98:99], 1.0 op_sel_hi:[1,0]
	v_pk_add_f32 v[100:101], v[100:101], 1.0 op_sel_hi:[1,0]
	v_pk_add_f32 v[86:87], v[86:87], 1.0 op_sel_hi:[1,0]
	v_pk_add_f32 v[88:89], v[88:89], 1.0 op_sel_hi:[1,0]
	v_pk_add_f32 v[82:83], v[82:83], 1.0 op_sel_hi:[1,0]
	v_pk_add_f32 v[84:85], v[84:85], 1.0 op_sel_hi:[1,0]
	v_rcp_f32_e32 v102, v102
	v_rcp_f32_e32 v103, v103
	v_rcp_f32_e32 v104, v104
	v_rcp_f32_e32 v105, v105
	v_rcp_f32_e32 v98, v98
	v_rcp_f32_e32 v99, v99
	v_rcp_f32_e32 v100, v100
	v_rcp_f32_e32 v101, v101
	v_rcp_f32_e32 v86, v86
	v_rcp_f32_e32 v87, v87
	v_rcp_f32_e32 v88, v88
	v_rcp_f32_e32 v89, v89
	v_rcp_f32_e32 v82, v82
	v_rcp_f32_e32 v83, v83
	v_rcp_f32_e32 v84, v84
	v_rcp_f32_e32 v85, v85
	v_cvt_pk_bf16_f32 v244, v102, v103
	v_cvt_pk_bf16_f32 v245, v104, v105
	v_cvt_pk_bf16_f32 v246, v98, v99
	v_cvt_pk_bf16_f32 v247, v100, v101
	global_store_dwordx4 v242, v[244:247], s[2:3]
	v_cvt_pk_bf16_f32 v248, v86, v87
	v_cvt_pk_bf16_f32 v249, v88, v89
	v_cvt_pk_bf16_f32 v250, v82, v83
	v_cvt_pk_bf16_f32 v251, v84, v85
	global_store_dwordx4 v242, v[248:251], s[2:3] offset:256
	v_add_u32_e32 v242, 0x10000, v242
	v_pk_fma_f32 v[78:79], v[78:79], v[168:169], v[110:111] op_sel_hi:[1,0,1]
	v_pk_fma_f32 v[80:81], v[80:81], v[168:169], v[112:113] op_sel_hi:[1,0,1]
	v_pk_fma_f32 v[74:75], v[74:75], v[168:169], v[106:107] op_sel_hi:[1,0,1]
	v_pk_fma_f32 v[76:77], v[76:77], v[168:169], v[108:109] op_sel_hi:[1,0,1]
	v_pk_fma_f32 v[70:71], v[70:71], v[168:169], v[94:95] op_sel_hi:[1,0,1]
	v_pk_fma_f32 v[72:73], v[72:73], v[168:169], v[96:97] op_sel_hi:[1,0,1]
	v_pk_fma_f32 v[66:67], v[66:67], v[168:169], v[90:91] op_sel_hi:[1,0,1]
	v_pk_fma_f32 v[68:69], v[68:69], v[168:169], v[92:93] op_sel_hi:[1,0,1]
	v_pk_mul_f32 v[78:79], v[78:79], s[100:101]
	v_pk_mul_f32 v[80:81], v[80:81], s[100:101]
	v_pk_mul_f32 v[74:75], v[74:75], s[100:101]
	v_pk_mul_f32 v[76:77], v[76:77], s[100:101]
	v_pk_mul_f32 v[70:71], v[70:71], s[100:101]
	v_pk_mul_f32 v[72:73], v[72:73], s[100:101]
	v_pk_mul_f32 v[66:67], v[66:67], s[100:101]
; __device__ __forceinline__ float sigmoidf_(float x) { return 1.0f / (1.0f + __builtin_amdgcn_exp2f(-1.4426950408889634f * x)); }
; #define EPIIN_PACK(w, a, b) do { (w).x = cvt_pk_bf16((a)[0], (a)[1]); (w).y = cvt_pk_bf16((a)[2], (a)[3]); (w).z = cvt_pk_bf16((b)[0], (b)[1]); (w).w = cvt_pk_bf16((b)[2], (b)[3]); } while (0)
;     __device__ __forceinline__ void operator()(const f32x4 (&acc_)[2][2][4][2], const Unit& u, int wr, int wc, int fr, int fq) const {
;     ...
; #pragma unroll
;             for (int ai = 0; ai < 2; ++ai)
; #pragma unroll
;                 for (int m = 0; m < 4; ++m) { const size_t row = rowb + ai * HALF + m * 16;
; #pragma unroll
;                     for (int bj = 0; bj < 2; ++bj) { f32x4 a = EPIIN_VAL(ai, bj, m, 0), b = EPIIN_VAL(ai, bj, m, 1);
; #pragma unroll
;                         for (int i = 0; i < 4; ++i) { a[i] = sigmoidf_(a[i]); b[i] = sigmoidf_(b[i]); }
;                         u32x4 w; EPIIN_PACK(w, a, b);
;                         *(u32x4*)(GATES + row * 2048 + (pn - 8) * 256 + bj * HALF + wc * 32 + fq * 8) = w; } }
	v_pk_mul_f32 v[68:69], v[68:69], s[100:101]
	v_exp_f32_e32 v78, v78
	v_exp_f32_e32 v79, v79
	v_exp_f32_e32 v80, v80
	v_exp_f32_e32 v81, v81
	v_exp_f32_e32 v74, v74
	v_exp_f32_e32 v75, v75
	v_exp_f32_e32 v76, v76
	v_exp_f32_e32 v77, v77
	v_exp_f32_e32 v70, v70
	v_exp_f32_e32 v71, v71
	v_exp_f32_e32 v72, v72
	v_exp_f32_e32 v73, v73
	v_exp_f32_e32 v66, v66
	v_exp_f32_e32 v67, v67
	v_exp_f32_e32 v68, v68
	v_exp_f32_e32 v69, v69
	v_pk_add_f32 v[78:79], v[78:79], 1.0 op_sel_hi:[1,0]
	v_pk_add_f32 v[80:81], v[80:81], 1.0 op_sel_hi:[1,0]
	v_pk_add_f32 v[74:75], v[74:75], 1.0 op_sel_hi:[1,0]
	v_pk_add_f32 v[76:77], v[76:77], 1.0 op_sel_hi:[1,0]
	v_pk_add_f32 v[70:71], v[70:71], 1.0 op_sel_hi:[1,0]
	v_pk_add_f32 v[72:73], v[72:73], 1.0 op_sel_hi:[1,0]
	v_pk_add_f32 v[66:67], v[66:67], 1.0 op_sel_hi:[1,0]
	v_pk_add_f32 v[68:69], v[68:69], 1.0 op_sel_hi:[1,0]
	v_rcp_f32_e32 v78, v78
	v_rcp_f32_e32 v79, v79
	v_rcp_f32_e32 v80, v80
	v_rcp_f32_e32 v81, v81
	v_rcp_f32_e32 v74, v74
	v_rcp_f32_e32 v75, v75
	v_rcp_f32_e32 v76, v76
	v_rcp_f32_e32 v77, v77
	v_rcp_f32_e32 v70, v70
	v_rcp_f32_e32 v71, v71
	v_rcp_f32_e32 v72, v72
	v_rcp_f32_e32 v73, v73
	v_rcp_f32_e32 v66, v66
	v_rcp_f32_e32 v67, v67
	v_rcp_f32_e32 v68, v68
	v_rcp_f32_e32 v69, v69
	v_cvt_pk_bf16_f32 v244, v78, v79
	v_cvt_pk_bf16_f32 v245, v80, v81
	v_cvt_pk_bf16_f32 v246, v74, v75
	v_cvt_pk_bf16_f32 v247, v76, v77
	global_store_dwordx4 v242, v[244:247], s[2:3]
	v_cvt_pk_bf16_f32 v248, v70, v71
	v_cvt_pk_bf16_f32 v249, v72, v73
	v_cvt_pk_bf16_f32 v250, v66, v67
	v_cvt_pk_bf16_f32 v251, v68, v69
	global_store_dwordx4 v242, v[248:251], s[2:3] offset:256
	v_add_u32_e32 v242, 0x50000, v242
	v_pk_fma_f32 v[62:63], v[62:63], v[166:167], v[110:111] op_sel_hi:[1,0,1]
	v_pk_fma_f32 v[64:65], v[64:65], v[166:167], v[112:113] op_sel_hi:[1,0,1]
	v_pk_fma_f32 v[58:59], v[58:59], v[166:167], v[106:107] op_sel_hi:[1,0,1]
	v_pk_fma_f32 v[60:61], v[60:61], v[166:167], v[108:109] op_sel_hi:[1,0,1]
	v_pk_fma_f32 v[54:55], v[54:55], v[166:167], v[94:95] op_sel_hi:[1,0,1]
	v_pk_fma_f32 v[56:57], v[56:57], v[166:167], v[96:97] op_sel_hi:[1,0,1]
	v_pk_fma_f32 v[50:51], v[50:51], v[166:167], v[90:91] op_sel_hi:[1,0,1]
	v_pk_fma_f32 v[52:53], v[52:53], v[166:167], v[92:93] op_sel_hi:[1,0,1]
	v_pk_mul_f32 v[62:63], v[62:63], s[100:101]
	v_pk_mul_f32 v[64:65], v[64:65], s[100:101]
	v_pk_mul_f32 v[58:59], v[58:59], s[100:101]
	v_pk_mul_f32 v[60:61], v[60:61], s[100:101]
	v_pk_mul_f32 v[54:55], v[54:55], s[100:101]
	v_pk_mul_f32 v[56:57], v[56:57], s[100:101]
	v_pk_mul_f32 v[50:51], v[50:51], s[100:101]
	v_pk_mul_f32 v[52:53], v[52:53], s[100:101]
	v_exp_f32_e32 v62, v62
	v_exp_f32_e32 v63, v63
	v_exp_f32_e32 v64, v64
	v_exp_f32_e32 v65, v65
	v_exp_f32_e32 v58, v58
	v_exp_f32_e32 v59, v59
	v_exp_f32_e32 v60, v60
	v_exp_f32_e32 v61, v61
	v_exp_f32_e32 v54, v54
	v_exp_f32_e32 v55, v55
	v_exp_f32_e32 v56, v56
	v_exp_f32_e32 v57, v57
	v_exp_f32_e32 v50, v50
	v_exp_f32_e32 v51, v51
	v_exp_f32_e32 v52, v52
	v_exp_f32_e32 v53, v53
	v_pk_add_f32 v[62:63], v[62:63], 1.0 op_sel_hi:[1,0]
	v_pk_add_f32 v[64:65], v[64:65], 1.0 op_sel_hi:[1,0]
	v_pk_add_f32 v[58:59], v[58:59], 1.0 op_sel_hi:[1,0]
	v_pk_add_f32 v[60:61], v[60:61], 1.0 op_sel_hi:[1,0]
	v_pk_add_f32 v[54:55], v[54:55], 1.0 op_sel_hi:[1,0]
	v_pk_add_f32 v[56:57], v[56:57], 1.0 op_sel_hi:[1,0]
	v_pk_add_f32 v[50:51], v[50:51], 1.0 op_sel_hi:[1,0]
	v_pk_add_f32 v[52:53], v[52:53], 1.0 op_sel_hi:[1,0]
	v_rcp_f32_e32 v62, v62
	v_rcp_f32_e32 v63, v63
	v_rcp_f32_e32 v64, v64
	v_rcp_f32_e32 v65, v65
	v_rcp_f32_e32 v58, v58
	v_rcp_f32_e32 v59, v59
	v_rcp_f32_e32 v60, v60
	v_rcp_f32_e32 v61, v61
	v_rcp_f32_e32 v54, v54
	v_rcp_f32_e32 v55, v55
	v_rcp_f32_e32 v56, v56
	v_rcp_f32_e32 v57, v57
	v_rcp_f32_e32 v50, v50
	v_rcp_f32_e32 v51, v51
	v_rcp_f32_e32 v52, v52
	v_rcp_f32_e32 v53, v53
	v_cvt_pk_bf16_f32 v244, v62, v63
	v_cvt_pk_bf16_f32 v245, v64, v65
	v_cvt_pk_bf16_f32 v246, v58, v59
	v_cvt_pk_bf16_f32 v247, v60, v61
	global_store_dwordx4 v242, v[244:247], s[2:3]
	v_cvt_pk_bf16_f32 v248, v54, v55
	v_cvt_pk_bf16_f32 v249, v56, v57
	v_cvt_pk_bf16_f32 v250, v50, v51
	v_cvt_pk_bf16_f32 v251, v52, v53
	global_store_dwordx4 v242, v[248:251], s[2:3] offset:256
	v_add_u32_e32 v242, 0x10000, v242
	v_pk_fma_f32 v[46:47], v[46:47], v[164:165], v[110:111] op_sel_hi:[1,0,1]
	v_pk_fma_f32 v[48:49], v[48:49], v[164:165], v[112:113] op_sel_hi:[1,0,1]
	v_pk_fma_f32 v[42:43], v[42:43], v[164:165], v[106:107] op_sel_hi:[1,0,1]
	v_pk_fma_f32 v[44:45], v[44:45], v[164:165], v[108:109] op_sel_hi:[1,0,1]
	v_pk_fma_f32 v[38:39], v[38:39], v[164:165], v[94:95] op_sel_hi:[1,0,1]
	v_pk_fma_f32 v[40:41], v[40:41], v[164:165], v[96:97] op_sel_hi:[1,0,1]
	v_pk_fma_f32 v[34:35], v[34:35], v[164:165], v[90:91] op_sel_hi:[1,0,1]
	v_pk_fma_f32 v[36:37], v[36:37], v[164:165], v[92:93] op_sel_hi:[1,0,1]
	v_pk_mul_f32 v[46:47], v[46:47], s[100:101]
	v_pk_mul_f32 v[48:49], v[48:49], s[100:101]
	v_pk_mul_f32 v[42:43], v[42:43], s[100:101]
	v_pk_mul_f32 v[44:45], v[44:45], s[100:101]
	v_pk_mul_f32 v[38:39], v[38:39], s[100:101]
	v_pk_mul_f32 v[40:41], v[40:41], s[100:101]
	v_pk_mul_f32 v[34:35], v[34:35], s[100:101]
	v_pk_mul_f32 v[36:37], v[36:37], s[100:101]
	v_exp_f32_e32 v46, v46
	v_exp_f32_e32 v47, v47
	v_exp_f32_e32 v48, v48
	v_exp_f32_e32 v49, v49
	v_exp_f32_e32 v42, v42
	v_exp_f32_e32 v43, v43
	v_exp_f32_e32 v44, v44
	v_exp_f32_e32 v45, v45
	v_exp_f32_e32 v38, v38
	v_exp_f32_e32 v39, v39
	v_exp_f32_e32 v40, v40
	v_exp_f32_e32 v41, v41
	v_exp_f32_e32 v34, v34
	v_exp_f32_e32 v35, v35
	v_exp_f32_e32 v36, v36
	v_exp_f32_e32 v37, v37
	v_pk_add_f32 v[46:47], v[46:47], 1.0 op_sel_hi:[1,0]
	v_pk_add_f32 v[48:49], v[48:49], 1.0 op_sel_hi:[1,0]
; __device__ __forceinline__ float sigmoidf_(float x) { return 1.0f / (1.0f + __builtin_amdgcn_exp2f(-1.4426950408889634f * x)); }
; #define EPIIN_PACK(w, a, b) do { (w).x = cvt_pk_bf16((a)[0], (a)[1]); (w).y = cvt_pk_bf16((a)[2], (a)[3]); (w).z = cvt_pk_bf16((b)[0], (b)[1]); (w).w = cvt_pk_bf16((b)[2], (b)[3]); } while (0)
;     __device__ __forceinline__ void operator()(const f32x4 (&acc_)[2][2][4][2], const Unit& u, int wr, int wc, int fr, int fq) const {
;     ...
; #pragma unroll
;             for (int ai = 0; ai < 2; ++ai)
; #pragma unroll
;                 for (int m = 0; m < 4; ++m) { const size_t row = rowb + ai * HALF + m * 16;
; #pragma unroll
;                     for (int bj = 0; bj < 2; ++bj) { f32x4 a = EPIIN_VAL(ai, bj, m, 0), b = EPIIN_VAL(ai, bj, m, 1);
; #pragma unroll
;                         for (int i = 0; i < 4; ++i) { a[i] = sigmoidf_(a[i]); b[i] = sigmoidf_(b[i]); }
;                         u32x4 w; EPIIN_PACK(w, a, b);
;                         *(u32x4*)(GATES + row * 2048 + (pn - 8) * 256 + bj * HALF + wc * 32 + fq * 8) = w; } }
	v_pk_add_f32 v[42:43], v[42:43], 1.0 op_sel_hi:[1,0]
	v_pk_add_f32 v[44:45], v[44:45], 1.0 op_sel_hi:[1,0]
	v_pk_add_f32 v[38:39], v[38:39], 1.0 op_sel_hi:[1,0]
	v_pk_add_f32 v[40:41], v[40:41], 1.0 op_sel_hi:[1,0]
	v_pk_add_f32 v[34:35], v[34:35], 1.0 op_sel_hi:[1,0]
	v_pk_add_f32 v[36:37], v[36:37], 1.0 op_sel_hi:[1,0]
	v_rcp_f32_e32 v46, v46
	v_rcp_f32_e32 v47, v47
	v_rcp_f32_e32 v48, v48
	v_rcp_f32_e32 v49, v49
	v_rcp_f32_e32 v42, v42
	v_rcp_f32_e32 v43, v43
	v_rcp_f32_e32 v44, v44
	v_rcp_f32_e32 v45, v45
	v_rcp_f32_e32 v38, v38
	v_rcp_f32_e32 v39, v39
	v_rcp_f32_e32 v40, v40
	v_rcp_f32_e32 v41, v41
	v_rcp_f32_e32 v34, v34
	v_rcp_f32_e32 v35, v35
	v_rcp_f32_e32 v36, v36
	v_rcp_f32_e32 v37, v37
	v_cvt_pk_bf16_f32 v244, v46, v47
	v_cvt_pk_bf16_f32 v245, v48, v49
	v_cvt_pk_bf16_f32 v246, v42, v43
	v_cvt_pk_bf16_f32 v247, v44, v45
	global_store_dwordx4 v242, v[244:247], s[2:3]
	v_cvt_pk_bf16_f32 v248, v38, v39
	v_cvt_pk_bf16_f32 v249, v40, v41
	v_cvt_pk_bf16_f32 v250, v34, v35
	v_cvt_pk_bf16_f32 v251, v36, v37
	global_store_dwordx4 v242, v[248:251], s[2:3] offset:256
	v_add_u32_e32 v242, 0x10000, v242
	v_pk_fma_f32 v[30:31], v[30:31], v[162:163], v[110:111] op_sel_hi:[1,0,1]
	v_pk_fma_f32 v[32:33], v[32:33], v[162:163], v[112:113] op_sel_hi:[1,0,1]
	v_pk_fma_f32 v[26:27], v[26:27], v[162:163], v[106:107] op_sel_hi:[1,0,1]
	v_pk_fma_f32 v[28:29], v[28:29], v[162:163], v[108:109] op_sel_hi:[1,0,1]
	v_pk_fma_f32 v[22:23], v[22:23], v[162:163], v[94:95] op_sel_hi:[1,0,1]
	v_pk_fma_f32 v[24:25], v[24:25], v[162:163], v[96:97] op_sel_hi:[1,0,1]
	v_pk_fma_f32 v[18:19], v[18:19], v[162:163], v[90:91] op_sel_hi:[1,0,1]
	v_pk_fma_f32 v[20:21], v[20:21], v[162:163], v[92:93] op_sel_hi:[1,0,1]
	v_pk_mul_f32 v[30:31], v[30:31], s[100:101]
	v_pk_mul_f32 v[32:33], v[32:33], s[100:101]
	v_pk_mul_f32 v[26:27], v[26:27], s[100:101]
	v_pk_mul_f32 v[28:29], v[28:29], s[100:101]
	v_pk_mul_f32 v[22:23], v[22:23], s[100:101]
	v_pk_mul_f32 v[24:25], v[24:25], s[100:101]
	v_pk_mul_f32 v[18:19], v[18:19], s[100:101]
	v_pk_mul_f32 v[20:21], v[20:21], s[100:101]
	v_exp_f32_e32 v30, v30
	v_exp_f32_e32 v31, v31
	v_exp_f32_e32 v32, v32
	v_exp_f32_e32 v33, v33
	v_exp_f32_e32 v26, v26
	v_exp_f32_e32 v27, v27
	v_exp_f32_e32 v28, v28
	v_exp_f32_e32 v29, v29
	v_exp_f32_e32 v22, v22
	v_exp_f32_e32 v23, v23
	v_exp_f32_e32 v24, v24
	v_exp_f32_e32 v25, v25
	v_exp_f32_e32 v18, v18
	v_exp_f32_e32 v19, v19
	v_exp_f32_e32 v20, v20
	v_exp_f32_e32 v21, v21
	v_pk_add_f32 v[30:31], v[30:31], 1.0 op_sel_hi:[1,0]
	v_pk_add_f32 v[32:33], v[32:33], 1.0 op_sel_hi:[1,0]
	v_pk_add_f32 v[26:27], v[26:27], 1.0 op_sel_hi:[1,0]
	v_pk_add_f32 v[28:29], v[28:29], 1.0 op_sel_hi:[1,0]
	v_pk_add_f32 v[22:23], v[22:23], 1.0 op_sel_hi:[1,0]
	v_pk_add_f32 v[24:25], v[24:25], 1.0 op_sel_hi:[1,0]
	v_pk_add_f32 v[18:19], v[18:19], 1.0 op_sel_hi:[1,0]
	v_pk_add_f32 v[20:21], v[20:21], 1.0 op_sel_hi:[1,0]
	v_rcp_f32_e32 v30, v30
	v_rcp_f32_e32 v31, v31
	v_rcp_f32_e32 v32, v32
	v_rcp_f32_e32 v33, v33
	v_rcp_f32_e32 v26, v26
	v_rcp_f32_e32 v27, v27
	v_rcp_f32_e32 v28, v28
	v_rcp_f32_e32 v29, v29
	v_rcp_f32_e32 v22, v22
	v_rcp_f32_e32 v23, v23
	v_rcp_f32_e32 v24, v24
	v_rcp_f32_e32 v25, v25
	v_rcp_f32_e32 v18, v18
	v_rcp_f32_e32 v19, v19
	v_rcp_f32_e32 v20, v20
	v_rcp_f32_e32 v21, v21
	v_cvt_pk_bf16_f32 v244, v30, v31
	v_cvt_pk_bf16_f32 v245, v32, v33
	v_cvt_pk_bf16_f32 v246, v26, v27
	v_cvt_pk_bf16_f32 v247, v28, v29
	global_store_dwordx4 v242, v[244:247], s[2:3]
	v_cvt_pk_bf16_f32 v248, v22, v23
	v_cvt_pk_bf16_f32 v249, v24, v25
	v_cvt_pk_bf16_f32 v250, v18, v19
	v_cvt_pk_bf16_f32 v251, v20, v21
	global_store_dwordx4 v242, v[248:251], s[2:3] offset:256
	v_add_u32_e32 v242, 0x10000, v242
	v_pk_fma_f32 v[14:15], v[14:15], v[160:161], v[110:111] op_sel_hi:[1,0,1]
	v_pk_fma_f32 v[16:17], v[16:17], v[160:161], v[112:113] op_sel_hi:[1,0,1]
	v_pk_fma_f32 v[10:11], v[10:11], v[160:161], v[106:107] op_sel_hi:[1,0,1]
	v_pk_fma_f32 v[12:13], v[12:13], v[160:161], v[108:109] op_sel_hi:[1,0,1]
	v_pk_fma_f32 v[6:7], v[6:7], v[160:161], v[94:95] op_sel_hi:[1,0,1]
	v_pk_fma_f32 v[8:9], v[8:9], v[160:161], v[96:97] op_sel_hi:[1,0,1]
	v_pk_fma_f32 v[2:3], v[2:3], v[160:161], v[90:91] op_sel_hi:[1,0,1]
	v_pk_fma_f32 v[4:5], v[4:5], v[160:161], v[92:93] op_sel_hi:[1,0,1]
	v_pk_mul_f32 v[14:15], v[14:15], s[100:101]
	v_pk_mul_f32 v[16:17], v[16:17], s[100:101]
	v_pk_mul_f32 v[10:11], v[10:11], s[100:101]
	v_pk_mul_f32 v[12:13], v[12:13], s[100:101]
	v_pk_mul_f32 v[6:7], v[6:7], s[100:101]
	v_pk_mul_f32 v[8:9], v[8:9], s[100:101]
	v_pk_mul_f32 v[2:3], v[2:3], s[100:101]
	v_pk_mul_f32 v[4:5], v[4:5], s[100:101]
	v_exp_f32_e32 v14, v14
	v_exp_f32_e32 v15, v15
	v_exp_f32_e32 v16, v16
	v_exp_f32_e32 v17, v17
	v_exp_f32_e32 v10, v10
	v_exp_f32_e32 v11, v11
	v_exp_f32_e32 v12, v12
	v_exp_f32_e32 v13, v13
	v_exp_f32_e32 v6, v6
	v_exp_f32_e32 v7, v7
	v_exp_f32_e32 v8, v8
	v_exp_f32_e32 v9, v9
	v_exp_f32_e32 v2, v2
	v_exp_f32_e32 v3, v3
	v_exp_f32_e32 v4, v4
	v_exp_f32_e32 v5, v5
	v_pk_add_f32 v[14:15], v[14:15], 1.0 op_sel_hi:[1,0]
	v_pk_add_f32 v[16:17], v[16:17], 1.0 op_sel_hi:[1,0]
	v_pk_add_f32 v[10:11], v[10:11], 1.0 op_sel_hi:[1,0]
	v_pk_add_f32 v[12:13], v[12:13], 1.0 op_sel_hi:[1,0]
	v_pk_add_f32 v[6:7], v[6:7], 1.0 op_sel_hi:[1,0]
	v_pk_add_f32 v[8:9], v[8:9], 1.0 op_sel_hi:[1,0]
	v_pk_add_f32 v[2:3], v[2:3], 1.0 op_sel_hi:[1,0]
	v_pk_add_f32 v[4:5], v[4:5], 1.0 op_sel_hi:[1,0]
	v_rcp_f32_e32 v14, v14
	v_rcp_f32_e32 v15, v15
	v_rcp_f32_e32 v16, v16
	v_rcp_f32_e32 v17, v17
	v_rcp_f32_e32 v10, v10
	v_rcp_f32_e32 v11, v11
	v_rcp_f32_e32 v12, v12
	v_rcp_f32_e32 v13, v13
	v_rcp_f32_e32 v6, v6
	v_rcp_f32_e32 v7, v7
	v_rcp_f32_e32 v8, v8
	v_rcp_f32_e32 v9, v9
	v_rcp_f32_e32 v2, v2
	v_rcp_f32_e32 v3, v3
	v_rcp_f32_e32 v4, v4
	v_rcp_f32_e32 v5, v5
	v_cvt_pk_bf16_f32 v244, v14, v15
	v_cvt_pk_bf16_f32 v245, v16, v17
	v_cvt_pk_bf16_f32 v246, v10, v11
	v_cvt_pk_bf16_f32 v247, v12, v13
	global_store_dwordx4 v242, v[244:247], s[2:3]
	v_cvt_pk_bf16_f32 v248, v6, v7
	v_cvt_pk_bf16_f32 v249, v8, v9
	v_cvt_pk_bf16_f32 v250, v2, v3
	v_cvt_pk_bf16_f32 v251, v4, v5
	global_store_dwordx4 v242, v[248:251], s[2:3] offset:256
	s_mov_b64 s[2:3], 0xb0000
	s_branch .LBB0_559
; __device__ __forceinline__ float sigmoidf_(float x) { return 1.0f / (1.0f + __builtin_amdgcn_exp2f(-1.4426950408889634f * x)); }
; #define EPIIN_PACK(w, a, b) do { (w).x = cvt_pk_bf16((a)[0], (a)[1]); (w).y = cvt_pk_bf16((a)[2], (a)[3]); (w).z = cvt_pk_bf16((b)[0], (b)[1]); (w).w = cvt_pk_bf16((b)[2], (b)[3]); } while (0)
;     __device__ __forceinline__ void operator()(const f32x4 (&acc_)[2][2][4][2], const Unit& u, int wr, int wc, int fr, int fq) const {
;     ...
; #pragma unroll
;             for (int ai = 0; ai < 2; ++ai)
; #pragma unroll
;                 for (int m = 0; m < 4; ++m) { const size_t row = rowb + ai * HALF + m * 16;
; #pragma unroll
;                     for (int bj = 0; bj < 2; ++bj) { f32x4 a = EPIIN_VAL(ai, bj, m, 0), b = EPIIN_VAL(ai, bj, m, 1);
; #pragma unroll
;                         for (int i = 0; i < 4; ++i) { a[i] = sigmoidf_(a[i]); b[i] = sigmoidf_(b[i]); }
;                         u32x4 w; EPIIN_PACK(w, a, b);
;                         *(u32x4*)(GATES + row * 2048 + (pn - 8) * 256 + bj * HALF + wc * 32 + fq * 8) = w; } }
	v_pk_fma_f32 v[182:183], v[142:143], v[174:175], v[110:111] op_sel_hi:[1,0,1]
	v_pk_fma_f32 v[180:181], v[144:145], v[174:175], v[112:113] op_sel_hi:[1,0,1]
	v_mul_f32_e32 v0, 0xbfb8aa3b, v182
	v_exp_f32_e32 v0, v0
	v_pk_fma_f32 v[178:179], v[140:141], v[174:175], v[108:109] op_sel_hi:[1,0,1]
	v_pk_fma_f32 v[184:185], v[138:139], v[174:175], v[106:107] op_sel_hi:[1,0,1]
	v_mul_f32_e32 v178, 0xbfb8aa3b, v178
	v_add_f32_e32 v0, 1.0, v0
	v_exp_f32_e32 v178, v178
	v_lshlrev_b64 v[176:177], 12, v[158:159]
	s_add_i32 s30, s68, 0xfffff800
	v_rcp_f32_e32 v0, v0
	s_nop 0
	v_mul_f32_e32 v169, 0xbfb8aa3b, v184
	v_exp_f32_e32 v169, v169
	v_add_f32_e32 v178, 1.0, v178
	v_add_f32_e32 v169, 1.0, v169
	v_rcp_f32_e32 v169, v169
	s_nop 0
	v_mul_f32_e32 v171, 0xbfb8aa3b, v183
	v_exp_f32_e32 v171, v171
	s_nop 0
	v_add_f32_e32 v171, 1.0, v171
	v_rcp_f32_e32 v171, v171
	s_nop 0
	v_mul_f32_e32 v173, 0xbfb8aa3b, v185
	v_exp_f32_e32 v173, v173
	s_nop 0
	v_add_f32_e32 v173, 1.0, v173
	v_rcp_f32_e32 v173, v173
	s_nop 0
	v_mul_f32_e32 v175, 0xbfb8aa3b, v180
	v_exp_f32_e32 v175, v175
	s_nop 0
	v_add_f32_e32 v175, 1.0, v175
	v_rcp_f32_e32 v175, v175
	s_nop 0
	v_rcp_f32_e32 v182, v178
	s_nop 0
	v_mul_f32_e32 v178, 0xbfb8aa3b, v181
	v_exp_f32_e32 v178, v178
	s_nop 0
	v_add_f32_e32 v178, 1.0, v178
	v_rcp_f32_e32 v180, v178
	s_nop 0
	v_mul_f32_e32 v178, 0xbfb8aa3b, v179
	v_exp_f32_e32 v178, v178
	s_nop 0
	v_add_f32_e32 v178, 1.0, v178
	v_readlane_b32 s2, v255, 47
	v_readlane_b32 s3, v255, 48
	v_lshl_add_u64 v[176:177], s[2:3], 0, v[176:177]
	v_rcp_f32_e32 v181, v178
	s_nop 0
	v_lshl_add_u64 v[176:177], s[30:31], 1, v[176:177]
	s_lshl_b32 s30, s50, 1
	v_cvt_pk_bf16_f32 v178, v0, v171
	v_cvt_pk_bf16_f32 v179, v175, v180
	v_cvt_pk_bf16_f32 v180, v169, v173
	v_cvt_pk_bf16_f32 v181, v182, v181
	v_lshl_add_u64 v[176:177], v[176:177], 0, s[30:31]
	v_lshlrev_b32_e32 v0, 1, v167
	v_pk_fma_f32 v[182:183], v[134:135], v[174:175], v[94:95] op_sel_hi:[1,0,1]
	v_lshl_add_u64 v[176:177], v[176:177], 0, v[0:1]
	v_mul_f32_e32 v0, 0xbfb8aa3b, v182
	v_exp_f32_e32 v0, v0
	global_store_dwordx4 v[176:177], v[178:181], off
	v_pk_fma_f32 v[184:185], v[130:131], v[174:175], v[90:91] op_sel_hi:[1,0,1]
	v_add_f32_e32 v0, 1.0, v0
	v_div_scale_f32 v169, s[2:3], v0, v0, 1.0
	v_rcp_f32_e32 v171, v169
	v_pk_fma_f32 v[180:181], v[136:137], v[174:175], v[96:97] op_sel_hi:[1,0,1]
	v_pk_fma_f32 v[178:179], v[132:133], v[174:175], v[92:93] op_sel_hi:[1,0,1]
	v_fma_f32 v173, -v169, v171, 1.0
	v_fmac_f32_e32 v171, v173, v171
	v_div_scale_f32 v173, vcc, 1.0, v0, 1.0
	v_mul_f32_e32 v175, v173, v171
	v_fma_f32 v182, -v169, v175, v173
	v_fmac_f32_e32 v175, v182, v171
	v_fma_f32 v169, -v169, v175, v173
	v_div_fmas_f32 v169, v169, v171, v175
	v_div_fixup_f32 v0, v169, v0, 1.0
	v_mul_f32_e32 v169, 0xbfb8aa3b, v184
	v_exp_f32_e32 v169, v169
	v_mul_f32_e32 v178, 0xbfb8aa3b, v178
	v_exp_f32_e32 v178, v178
	v_add_f32_e32 v169, 1.0, v169
	v_add_f32_e32 v178, 1.0, v178
	v_rcp_f32_e32 v169, v169
	s_nop 0
	v_mul_f32_e32 v171, 0xbfb8aa3b, v183
	v_exp_f32_e32 v171, v171
	s_nop 0
	v_add_f32_e32 v171, 1.0, v171
	v_rcp_f32_e32 v171, v171
	s_nop 0
	v_mul_f32_e32 v173, 0xbfb8aa3b, v185
	v_exp_f32_e32 v173, v173
	s_nop 0
	v_add_f32_e32 v173, 1.0, v173
	v_rcp_f32_e32 v173, v173
	s_nop 0
	v_mul_f32_e32 v175, 0xbfb8aa3b, v180
	v_exp_f32_e32 v175, v175
	s_nop 0
	v_add_f32_e32 v175, 1.0, v175
	v_rcp_f32_e32 v175, v175
	s_nop 0
	v_rcp_f32_e32 v182, v178
	s_nop 0
	v_mul_f32_e32 v178, 0xbfb8aa3b, v181
	v_exp_f32_e32 v178, v178
	s_nop 0
	v_add_f32_e32 v178, 1.0, v178
	v_rcp_f32_e32 v180, v178
	s_nop 0
	v_mul_f32_e32 v178, 0xbfb8aa3b, v179
	v_exp_f32_e32 v178, v178
	s_nop 0
	v_add_f32_e32 v178, 1.0, v178
	v_rcp_f32_e32 v181, v178
	s_nop 0
	v_cvt_pk_bf16_f32 v178, v0, v171
	v_cvt_pk_bf16_f32 v179, v175, v180
	v_cvt_pk_bf16_f32 v180, v169, v173
	v_cvt_pk_bf16_f32 v181, v182, v181
	v_pk_fma_f32 v[182:183], v[126:127], v[172:173], v[110:111] op_sel_hi:[1,0,1]
	global_store_dwordx4 v[176:177], v[178:181], off offset:256
	v_mul_f32_e32 v0, 0xbfb8aa3b, v182
	v_exp_f32_e32 v0, v0
	v_pk_fma_f32 v[180:181], v[128:129], v[172:173], v[112:113] op_sel_hi:[1,0,1]
	v_pk_fma_f32 v[178:179], v[124:125], v[172:173], v[108:109] op_sel_hi:[1,0,1]
	v_pk_fma_f32 v[184:185], v[122:123], v[172:173], v[106:107] op_sel_hi:[1,0,1]
	v_add_f32_e32 v0, 1.0, v0
	v_mul_f32_e32 v178, 0xbfb8aa3b, v178
	v_exp_f32_e32 v178, v178
	v_mul_f32_e32 v179, 0xbfb8aa3b, v179
	v_rcp_f32_e32 v0, v0
	s_nop 0
	v_mul_f32_e32 v169, 0xbfb8aa3b, v184
	v_exp_f32_e32 v169, v169
	v_add_f32_e32 v178, 1.0, v178
	v_exp_f32_e32 v179, v179
	v_add_f32_e32 v169, 1.0, v169
	v_add_f32_e32 v179, 1.0, v179
	v_rcp_f32_e32 v169, v169
	s_nop 0
	v_mul_f32_e32 v171, 0xbfb8aa3b, v183
	v_exp_f32_e32 v171, v171
	s_nop 0
	v_add_f32_e32 v171, 1.0, v171
	v_rcp_f32_e32 v171, v171
	s_nop 0
	v_mul_f32_e32 v173, 0xbfb8aa3b, v185
	v_exp_f32_e32 v173, v173
	s_nop 0
	v_add_f32_e32 v173, 1.0, v173
	v_rcp_f32_e32 v173, v173
	s_nop 0
	v_mul_f32_e32 v175, 0xbfb8aa3b, v180
	v_exp_f32_e32 v175, v175
	v_pk_fma_f32 v[186:187], v[114:115], v[172:173], v[90:91] op_sel_hi:[1,0,1]
	v_add_f32_e32 v175, 1.0, v175
	v_rcp_f32_e32 v175, v175
	s_nop 0
	v_rcp_f32_e32 v178, v178
	s_nop 0
	v_mul_f32_e32 v180, 0xbfb8aa3b, v181
	v_exp_f32_e32 v180, v180
	s_nop 0
	v_add_f32_e32 v180, 1.0, v180
	v_rcp_f32_e32 v181, v180
	s_nop 0
	s_mov_b64 s[2:3], 0x10000
	v_rcp_f32_e32 v179, v179
	s_nop 0
	v_cvt_pk_bf16_f32 v180, v0, v171
	v_cvt_pk_bf16_f32 v181, v175, v181
	v_cvt_pk_bf16_f32 v182, v169, v173
	v_cvt_pk_bf16_f32 v183, v178, v179
	v_lshl_add_u64 v[178:179], v[176:177], 0, s[2:3]
	s_mov_b32 s2, 0x10000
	v_add_co_u32_e32 v184, vcc, s2, v176
	s_nop 1
; __device__ __forceinline__ float sigmoidf_(float x) { return 1.0f / (1.0f + __builtin_amdgcn_exp2f(-1.4426950408889634f * x)); }
; #define EPIIN_PACK(w, a, b) do { (w).x = cvt_pk_bf16((a)[0], (a)[1]); (w).y = cvt_pk_bf16((a)[2], (a)[3]); (w).z = cvt_pk_bf16((b)[0], (b)[1]); (w).w = cvt_pk_bf16((b)[2], (b)[3]); } while (0)
;     __device__ __forceinline__ void operator()(const f32x4 (&acc_)[2][2][4][2], const Unit& u, int wr, int wc, int fr, int fq) const {
;     ...
; #pragma unroll
;             for (int ai = 0; ai < 2; ++ai)
; #pragma unroll
;                 for (int m = 0; m < 4; ++m) { const size_t row = rowb + ai * HALF + m * 16;
; #pragma unroll
;                     for (int bj = 0; bj < 2; ++bj) { f32x4 a = EPIIN_VAL(ai, bj, m, 0), b = EPIIN_VAL(ai, bj, m, 1);
; #pragma unroll
;                         for (int i = 0; i < 4; ++i) { a[i] = sigmoidf_(a[i]); b[i] = sigmoidf_(b[i]); }
;                         u32x4 w; EPIIN_PACK(w, a, b);
;                         *(u32x4*)(GATES + row * 2048 + (pn - 8) * 256 + bj * HALF + wc * 32 + fq * 8) = w; } }
	v_addc_co_u32_e32 v185, vcc, 0, v177, vcc
	global_store_dwordx4 v[184:185], v[180:183], off
	v_pk_fma_f32 v[184:185], v[118:119], v[172:173], v[94:95] op_sel_hi:[1,0,1]
	s_nop 0
	v_mul_f32_e32 v0, 0xbfb8aa3b, v184
	v_exp_f32_e32 v0, v0
	v_pk_fma_f32 v[182:183], v[120:121], v[172:173], v[96:97] op_sel_hi:[1,0,1]
	v_pk_fma_f32 v[180:181], v[116:117], v[172:173], v[92:93] op_sel_hi:[1,0,1]
	v_add_f32_e32 v0, 1.0, v0
	v_mul_f32_e32 v180, 0xbfb8aa3b, v180
	v_exp_f32_e32 v180, v180
	v_rcp_f32_e32 v0, v0
	s_nop 0
	v_mul_f32_e32 v169, 0xbfb8aa3b, v186
	v_exp_f32_e32 v169, v169
	v_add_f32_e32 v180, 1.0, v180
	v_add_f32_e32 v169, 1.0, v169
	v_rcp_f32_e32 v169, v169
	s_nop 0
	v_mul_f32_e32 v171, 0xbfb8aa3b, v185
	v_exp_f32_e32 v171, v171
	s_nop 0
	v_add_f32_e32 v171, 1.0, v171
	v_rcp_f32_e32 v171, v171
	s_nop 0
	v_mul_f32_e32 v173, 0xbfb8aa3b, v187
	v_exp_f32_e32 v173, v173
	s_nop 0
	v_add_f32_e32 v173, 1.0, v173
	v_rcp_f32_e32 v173, v173
	s_nop 0
	v_mul_f32_e32 v175, 0xbfb8aa3b, v182
	v_exp_f32_e32 v175, v175
	s_nop 0
	v_add_f32_e32 v175, 1.0, v175
	v_rcp_f32_e32 v175, v175
	s_nop 0
	v_rcp_f32_e32 v184, v180
	s_nop 0
	v_mul_f32_e32 v180, 0xbfb8aa3b, v183
	v_exp_f32_e32 v180, v180
	s_nop 0
	v_add_f32_e32 v180, 1.0, v180
	v_rcp_f32_e32 v182, v180
	s_nop 0
	v_mul_f32_e32 v180, 0xbfb8aa3b, v181
	v_exp_f32_e32 v180, v180
	s_nop 0
	v_add_f32_e32 v180, 1.0, v180
	v_rcp_f32_e32 v183, v180
	s_nop 0
	v_cvt_pk_bf16_f32 v180, v0, v171
	v_cvt_pk_bf16_f32 v181, v175, v182
	v_cvt_pk_bf16_f32 v182, v169, v173
	v_cvt_pk_bf16_f32 v183, v184, v183
	global_store_dwordx4 v[178:179], v[180:183], off offset:256
	v_pk_fma_f32 v[178:179], v[100:101], v[170:171], v[108:109] op_sel_hi:[1,0,1]
	v_pk_fma_f32 v[184:185], v[98:99], v[170:171], v[106:107] op_sel_hi:[1,0,1]
	v_pk_fma_f32 v[182:183], v[102:103], v[170:171], v[110:111] op_sel_hi:[1,0,1]
	v_pk_fma_f32 v[180:181], v[104:105], v[170:171], v[112:113] op_sel_hi:[1,0,1]
	v_mul_f32_e32 v0, 0xbfb8aa3b, v182
	v_exp_f32_e32 v0, v0
	v_mul_f32_e32 v178, 0xbfb8aa3b, v178
	v_exp_f32_e32 v178, v178
	v_mul_f32_e32 v179, 0xbfb8aa3b, v179
	v_add_f32_e32 v0, 1.0, v0
	v_add_f32_e32 v178, 1.0, v178
	v_exp_f32_e32 v179, v179
	v_rcp_f32_e32 v0, v0
	s_nop 0
	v_mul_f32_e32 v169, 0xbfb8aa3b, v184
	v_exp_f32_e32 v169, v169
	v_add_f32_e32 v179, 1.0, v179
	v_add_f32_e32 v169, 1.0, v169
	v_rcp_f32_e32 v169, v169
	s_nop 0
	v_mul_f32_e32 v171, 0xbfb8aa3b, v183
	v_exp_f32_e32 v171, v171
	s_nop 0
	v_add_f32_e32 v171, 1.0, v171
	v_rcp_f32_e32 v171, v171
	s_nop 0
	v_mul_f32_e32 v173, 0xbfb8aa3b, v185
	v_exp_f32_e32 v173, v173
	v_pk_fma_f32 v[186:187], v[82:83], v[170:171], v[90:91] op_sel_hi:[1,0,1]
	v_add_f32_e32 v173, 1.0, v173
	v_rcp_f32_e32 v173, v173
	s_nop 0
	v_mul_f32_e32 v175, 0xbfb8aa3b, v180
	v_exp_f32_e32 v175, v175
	s_nop 0
	v_add_f32_e32 v175, 1.0, v175
	v_rcp_f32_e32 v175, v175
	s_nop 0
	v_rcp_f32_e32 v178, v178
	s_nop 0
	v_mul_f32_e32 v180, 0xbfb8aa3b, v181
	v_exp_f32_e32 v180, v180
	s_nop 0
	v_add_f32_e32 v180, 1.0, v180
	v_rcp_f32_e32 v181, v180
	s_nop 0
	s_mov_b64 s[2:3], 0x20000
	v_rcp_f32_e32 v179, v179
	s_nop 0
	v_cvt_pk_bf16_f32 v180, v0, v171
	v_cvt_pk_bf16_f32 v181, v175, v181
	v_cvt_pk_bf16_f32 v182, v169, v173
	v_cvt_pk_bf16_f32 v183, v178, v179
	v_lshl_add_u64 v[178:179], v[176:177], 0, s[2:3]
	s_mov_b32 s2, 0x20000
	v_add_co_u32_e32 v184, vcc, s2, v176
	s_nop 1
	v_addc_co_u32_e32 v185, vcc, 0, v177, vcc
	global_store_dwordx4 v[184:185], v[180:183], off
	v_pk_fma_f32 v[184:185], v[86:87], v[170:171], v[94:95] op_sel_hi:[1,0,1]
	s_nop 0
	v_mul_f32_e32 v0, 0xbfb8aa3b, v184
	v_exp_f32_e32 v0, v0
	v_pk_fma_f32 v[182:183], v[88:89], v[170:171], v[96:97] op_sel_hi:[1,0,1]
	v_pk_fma_f32 v[180:181], v[84:85], v[170:171], v[92:93] op_sel_hi:[1,0,1]
	v_add_f32_e32 v0, 1.0, v0
	v_mul_f32_e32 v180, 0xbfb8aa3b, v180
	v_exp_f32_e32 v180, v180
	v_rcp_f32_e32 v0, v0
	s_nop 0
	v_mul_f32_e32 v169, 0xbfb8aa3b, v186
	v_exp_f32_e32 v169, v169
	v_add_f32_e32 v180, 1.0, v180
	v_add_f32_e32 v169, 1.0, v169
	v_rcp_f32_e32 v169, v169
	s_nop 0
	v_mul_f32_e32 v171, 0xbfb8aa3b, v185
	v_exp_f32_e32 v171, v171
	s_nop 0
	v_add_f32_e32 v171, 1.0, v171
	v_rcp_f32_e32 v171, v171
	s_nop 0
	v_mul_f32_e32 v173, 0xbfb8aa3b, v187
	v_exp_f32_e32 v173, v173
	s_nop 0
	v_add_f32_e32 v173, 1.0, v173
	v_rcp_f32_e32 v173, v173
	s_nop 0
	v_mul_f32_e32 v175, 0xbfb8aa3b, v182
	v_exp_f32_e32 v175, v175
	s_nop 0
	v_add_f32_e32 v175, 1.0, v175
	v_rcp_f32_e32 v175, v175
	s_nop 0
	v_rcp_f32_e32 v184, v180
	s_nop 0
	v_mul_f32_e32 v180, 0xbfb8aa3b, v183
	v_exp_f32_e32 v180, v180
	s_nop 0
	v_add_f32_e32 v180, 1.0, v180
	v_rcp_f32_e32 v182, v180
	s_nop 0
	v_mul_f32_e32 v180, 0xbfb8aa3b, v181
	v_exp_f32_e32 v180, v180
	s_nop 0
	v_add_f32_e32 v180, 1.0, v180
	v_rcp_f32_e32 v183, v180
	s_nop 0
	v_cvt_pk_bf16_f32 v180, v0, v171
	v_cvt_pk_bf16_f32 v181, v175, v182
	v_cvt_pk_bf16_f32 v182, v169, v173
	v_cvt_pk_bf16_f32 v183, v184, v183
	global_store_dwordx4 v[178:179], v[180:183], off offset:256
	v_pk_fma_f32 v[178:179], v[76:77], v[168:169], v[108:109] op_sel_hi:[1,0,1]
	v_pk_fma_f32 v[184:185], v[74:75], v[168:169], v[106:107] op_sel_hi:[1,0,1]
	v_pk_fma_f32 v[182:183], v[78:79], v[168:169], v[110:111] op_sel_hi:[1,0,1]
	v_pk_fma_f32 v[180:181], v[80:81], v[168:169], v[112:113] op_sel_hi:[1,0,1]
	v_mul_f32_e32 v0, 0xbfb8aa3b, v182
	v_exp_f32_e32 v0, v0
	v_mul_f32_e32 v178, 0xbfb8aa3b, v178
	v_exp_f32_e32 v178, v178
	v_mul_f32_e32 v179, 0xbfb8aa3b, v179
	v_add_f32_e32 v0, 1.0, v0
	v_add_f32_e32 v178, 1.0, v178
	v_exp_f32_e32 v179, v179
	v_rcp_f32_e32 v0, v0
	s_nop 0
	v_mul_f32_e32 v169, 0xbfb8aa3b, v184
	v_exp_f32_e32 v169, v169
	v_add_f32_e32 v179, 1.0, v179
	v_add_f32_e32 v169, 1.0, v169
; __device__ __forceinline__ float sigmoidf_(float x) { return 1.0f / (1.0f + __builtin_amdgcn_exp2f(-1.4426950408889634f * x)); }
; #define EPIIN_PACK(w, a, b) do { (w).x = cvt_pk_bf16((a)[0], (a)[1]); (w).y = cvt_pk_bf16((a)[2], (a)[3]); (w).z = cvt_pk_bf16((b)[0], (b)[1]); (w).w = cvt_pk_bf16((b)[2], (b)[3]); } while (0)
;     __device__ __forceinline__ void operator()(const f32x4 (&acc_)[2][2][4][2], const Unit& u, int wr, int wc, int fr, int fq) const {
;     ...
; #pragma unroll
;             for (int ai = 0; ai < 2; ++ai)
; #pragma unroll
;                 for (int m = 0; m < 4; ++m) { const size_t row = rowb + ai * HALF + m * 16;
; #pragma unroll
;                     for (int bj = 0; bj < 2; ++bj) { f32x4 a = EPIIN_VAL(ai, bj, m, 0), b = EPIIN_VAL(ai, bj, m, 1);
; #pragma unroll
;                         for (int i = 0; i < 4; ++i) { a[i] = sigmoidf_(a[i]); b[i] = sigmoidf_(b[i]); }
;                         u32x4 w; EPIIN_PACK(w, a, b);
;                         *(u32x4*)(GATES + row * 2048 + (pn - 8) * 256 + bj * HALF + wc * 32 + fq * 8) = w; } }
	v_rcp_f32_e32 v169, v169
	s_nop 0
	v_mul_f32_e32 v171, 0xbfb8aa3b, v183
	v_exp_f32_e32 v171, v171
	v_pk_fma_f32 v[186:187], v[66:67], v[168:169], v[90:91] op_sel_hi:[1,0,1]
	v_add_f32_e32 v171, 1.0, v171
	v_rcp_f32_e32 v171, v171
	s_nop 0
	v_mul_f32_e32 v173, 0xbfb8aa3b, v185
	v_exp_f32_e32 v173, v173
	s_nop 0
	v_add_f32_e32 v173, 1.0, v173
	v_rcp_f32_e32 v173, v173
	s_nop 0
	v_mul_f32_e32 v175, 0xbfb8aa3b, v180
	v_exp_f32_e32 v175, v175
	s_nop 0
	v_add_f32_e32 v175, 1.0, v175
	v_rcp_f32_e32 v175, v175
	s_nop 0
	v_rcp_f32_e32 v178, v178
	s_nop 0
	v_mul_f32_e32 v180, 0xbfb8aa3b, v181
	v_exp_f32_e32 v180, v180
	s_nop 0
	v_add_f32_e32 v180, 1.0, v180
	v_rcp_f32_e32 v181, v180
	s_nop 0
	s_mov_b64 s[2:3], 0x30000
	v_rcp_f32_e32 v179, v179
	s_nop 0
	v_cvt_pk_bf16_f32 v180, v0, v171
	v_cvt_pk_bf16_f32 v181, v175, v181
	v_cvt_pk_bf16_f32 v182, v169, v173
	v_cvt_pk_bf16_f32 v183, v178, v179
	v_lshl_add_u64 v[178:179], v[176:177], 0, s[2:3]
	s_mov_b32 s2, 0x30000
	v_add_co_u32_e32 v184, vcc, s2, v176
	s_nop 1
	v_addc_co_u32_e32 v185, vcc, 0, v177, vcc
	global_store_dwordx4 v[184:185], v[180:183], off
	v_pk_fma_f32 v[184:185], v[70:71], v[168:169], v[94:95] op_sel_hi:[1,0,1]
	s_nop 0
	v_mul_f32_e32 v0, 0xbfb8aa3b, v184
	v_exp_f32_e32 v0, v0
	v_pk_fma_f32 v[182:183], v[72:73], v[168:169], v[96:97] op_sel_hi:[1,0,1]
	v_pk_fma_f32 v[180:181], v[68:69], v[168:169], v[92:93] op_sel_hi:[1,0,1]
	v_add_f32_e32 v0, 1.0, v0
	v_mul_f32_e32 v180, 0xbfb8aa3b, v180
	v_exp_f32_e32 v180, v180
	v_rcp_f32_e32 v0, v0
	s_nop 0
	v_mul_f32_e32 v169, 0xbfb8aa3b, v186
	v_exp_f32_e32 v169, v169
	v_add_f32_e32 v180, 1.0, v180
	v_add_f32_e32 v169, 1.0, v169
	v_rcp_f32_e32 v169, v169
	s_nop 0
	v_mul_f32_e32 v171, 0xbfb8aa3b, v185
	v_exp_f32_e32 v171, v171
	s_nop 0
	v_add_f32_e32 v171, 1.0, v171
	v_rcp_f32_e32 v171, v171
	s_nop 0
	v_mul_f32_e32 v173, 0xbfb8aa3b, v187
	v_exp_f32_e32 v173, v173
	s_nop 0
	v_add_f32_e32 v173, 1.0, v173
	v_rcp_f32_e32 v173, v173
	s_nop 0
	v_mul_f32_e32 v175, 0xbfb8aa3b, v182
	v_exp_f32_e32 v175, v175
	s_nop 0
	v_add_f32_e32 v175, 1.0, v175
	v_rcp_f32_e32 v175, v175
	s_nop 0
	v_rcp_f32_e32 v184, v180
	s_nop 0
	v_mul_f32_e32 v180, 0xbfb8aa3b, v183
	v_exp_f32_e32 v180, v180
	s_nop 0
	v_add_f32_e32 v180, 1.0, v180
	v_rcp_f32_e32 v182, v180
	s_nop 0
	v_mul_f32_e32 v180, 0xbfb8aa3b, v181
	v_exp_f32_e32 v180, v180
	s_nop 0
	v_add_f32_e32 v180, 1.0, v180
	v_rcp_f32_e32 v183, v180
	s_nop 0
	v_cvt_pk_bf16_f32 v180, v0, v171
	v_cvt_pk_bf16_f32 v181, v175, v182
	v_cvt_pk_bf16_f32 v182, v169, v173
	v_cvt_pk_bf16_f32 v183, v184, v183
	global_store_dwordx4 v[178:179], v[180:183], off offset:256
	v_pk_fma_f32 v[184:185], v[58:59], v[166:167], v[106:107] op_sel_hi:[1,0,1]
	v_pk_fma_f32 v[178:179], v[60:61], v[166:167], v[108:109] op_sel_hi:[1,0,1]
	v_pk_fma_f32 v[182:183], v[62:63], v[166:167], v[110:111] op_sel_hi:[1,0,1]
	v_pk_fma_f32 v[180:181], v[64:65], v[166:167], v[112:113] op_sel_hi:[1,0,1]
	v_mul_f32_e32 v0, 0xbfb8aa3b, v182
	v_exp_f32_e32 v0, v0
	v_mul_f32_e32 v178, 0xbfb8aa3b, v178
	v_exp_f32_e32 v178, v178
	v_mul_f32_e32 v179, 0xbfb8aa3b, v179
	v_add_f32_e32 v0, 1.0, v0
	v_add_f32_e32 v178, 1.0, v178
	v_exp_f32_e32 v179, v179
	v_pk_fma_f32 v[186:187], v[50:51], v[166:167], v[90:91] op_sel_hi:[1,0,1]
	v_rcp_f32_e32 v0, v0
	s_nop 0
	v_mul_f32_e32 v169, 0xbfb8aa3b, v184
	v_exp_f32_e32 v169, v169
	v_add_f32_e32 v179, 1.0, v179
	v_add_f32_e32 v169, 1.0, v169
	v_rcp_f32_e32 v169, v169
	s_nop 0
	v_mul_f32_e32 v171, 0xbfb8aa3b, v183
	v_exp_f32_e32 v171, v171
	s_nop 0
	v_add_f32_e32 v171, 1.0, v171
	v_rcp_f32_e32 v171, v171
	s_nop 0
	v_mul_f32_e32 v173, 0xbfb8aa3b, v185
	v_exp_f32_e32 v173, v173
	s_nop 0
	v_add_f32_e32 v173, 1.0, v173
	v_rcp_f32_e32 v173, v173
	s_nop 0
	v_mul_f32_e32 v175, 0xbfb8aa3b, v180
	v_exp_f32_e32 v175, v175
	s_nop 0
	v_add_f32_e32 v175, 1.0, v175
	v_rcp_f32_e32 v175, v175
	s_nop 0
	v_rcp_f32_e32 v178, v178
	s_nop 0
	v_mul_f32_e32 v180, 0xbfb8aa3b, v181
	v_exp_f32_e32 v180, v180
	s_nop 0
	v_add_f32_e32 v180, 1.0, v180
	v_rcp_f32_e32 v181, v180
	s_nop 0
	s_mov_b64 s[2:3], 0x80000
	v_rcp_f32_e32 v179, v179
	s_nop 0
	v_cvt_pk_bf16_f32 v180, v0, v171
	v_cvt_pk_bf16_f32 v181, v175, v181
	v_cvt_pk_bf16_f32 v182, v169, v173
	v_cvt_pk_bf16_f32 v183, v178, v179
	v_lshl_add_u64 v[178:179], v[176:177], 0, s[2:3]
	s_mov_b32 s2, 0x80000
	v_add_co_u32_e32 v184, vcc, s2, v176
	s_nop 1
	v_addc_co_u32_e32 v185, vcc, 0, v177, vcc
	global_store_dwordx4 v[184:185], v[180:183], off
	v_pk_fma_f32 v[184:185], v[54:55], v[166:167], v[94:95] op_sel_hi:[1,0,1]
	s_nop 0
	v_mul_f32_e32 v0, 0xbfb8aa3b, v184
	v_exp_f32_e32 v0, v0
	v_pk_fma_f32 v[182:183], v[56:57], v[166:167], v[96:97] op_sel_hi:[1,0,1]
	v_pk_fma_f32 v[180:181], v[52:53], v[166:167], v[92:93] op_sel_hi:[1,0,1]
	v_add_f32_e32 v0, 1.0, v0
	v_mul_f32_e32 v180, 0xbfb8aa3b, v180
	v_exp_f32_e32 v180, v180
	v_rcp_f32_e32 v0, v0
	s_nop 0
	v_mul_f32_e32 v169, 0xbfb8aa3b, v186
	v_exp_f32_e32 v169, v169
	v_add_f32_e32 v180, 1.0, v180
	v_add_f32_e32 v169, 1.0, v169
	v_rcp_f32_e32 v169, v169
	s_nop 0
	v_mul_f32_e32 v171, 0xbfb8aa3b, v185
	v_exp_f32_e32 v171, v171
	s_nop 0
	v_add_f32_e32 v171, 1.0, v171
	v_rcp_f32_e32 v171, v171
	s_nop 0
	v_mul_f32_e32 v173, 0xbfb8aa3b, v187
	v_exp_f32_e32 v173, v173
	s_nop 0
	v_add_f32_e32 v173, 1.0, v173
	v_rcp_f32_e32 v173, v173
	s_nop 0
	v_mul_f32_e32 v175, 0xbfb8aa3b, v182
	v_exp_f32_e32 v175, v175
	s_nop 0
	v_add_f32_e32 v175, 1.0, v175
	v_rcp_f32_e32 v175, v175
	s_nop 0
	v_rcp_f32_e32 v184, v180
	s_nop 0
	v_mul_f32_e32 v180, 0xbfb8aa3b, v183
	v_exp_f32_e32 v180, v180
	s_nop 0
	v_add_f32_e32 v180, 1.0, v180
	v_rcp_f32_e32 v182, v180
	s_nop 0
	v_mul_f32_e32 v180, 0xbfb8aa3b, v181
; __device__ __forceinline__ float sigmoidf_(float x) { return 1.0f / (1.0f + __builtin_amdgcn_exp2f(-1.4426950408889634f * x)); }
; #define EPIIN_PACK(w, a, b) do { (w).x = cvt_pk_bf16((a)[0], (a)[1]); (w).y = cvt_pk_bf16((a)[2], (a)[3]); (w).z = cvt_pk_bf16((b)[0], (b)[1]); (w).w = cvt_pk_bf16((b)[2], (b)[3]); } while (0)
;     __device__ __forceinline__ void operator()(const f32x4 (&acc_)[2][2][4][2], const Unit& u, int wr, int wc, int fr, int fq) const {
;     ...
; #pragma unroll
;             for (int ai = 0; ai < 2; ++ai)
; #pragma unroll
;                 for (int m = 0; m < 4; ++m) { const size_t row = rowb + ai * HALF + m * 16;
; #pragma unroll
;                     for (int bj = 0; bj < 2; ++bj) { f32x4 a = EPIIN_VAL(ai, bj, m, 0), b = EPIIN_VAL(ai, bj, m, 1);
; #pragma unroll
;                         for (int i = 0; i < 4; ++i) { a[i] = sigmoidf_(a[i]); b[i] = sigmoidf_(b[i]); }
;                         u32x4 w; EPIIN_PACK(w, a, b);
;                         *(u32x4*)(GATES + row * 2048 + (pn - 8) * 256 + bj * HALF + wc * 32 + fq * 8) = w; } }
	v_exp_f32_e32 v180, v180
	s_nop 0
	v_add_f32_e32 v180, 1.0, v180
	v_rcp_f32_e32 v183, v180
	s_nop 0
	v_cvt_pk_bf16_f32 v180, v0, v171
	v_cvt_pk_bf16_f32 v181, v175, v182
	v_cvt_pk_bf16_f32 v182, v169, v173
	v_cvt_pk_bf16_f32 v183, v184, v183
	global_store_dwordx4 v[178:179], v[180:183], off offset:256
	v_pk_fma_f32 v[184:185], v[42:43], v[164:165], v[106:107] op_sel_hi:[1,0,1]
	v_pk_fma_f32 v[178:179], v[44:45], v[164:165], v[108:109] op_sel_hi:[1,0,1]
	v_pk_fma_f32 v[182:183], v[46:47], v[164:165], v[110:111] op_sel_hi:[1,0,1]
	v_pk_fma_f32 v[180:181], v[48:49], v[164:165], v[112:113] op_sel_hi:[1,0,1]
	v_mul_f32_e32 v0, 0xbfb8aa3b, v182
	v_exp_f32_e32 v0, v0
	v_mul_f32_e32 v178, 0xbfb8aa3b, v178
	v_exp_f32_e32 v178, v178
	v_mul_f32_e32 v179, 0xbfb8aa3b, v179
	v_add_f32_e32 v0, 1.0, v0
	v_add_f32_e32 v178, 1.0, v178
	v_exp_f32_e32 v179, v179
	v_pk_fma_f32 v[186:187], v[34:35], v[164:165], v[90:91] op_sel_hi:[1,0,1]
	v_rcp_f32_e32 v0, v0
	s_nop 0
	v_mul_f32_e32 v169, 0xbfb8aa3b, v184
	v_exp_f32_e32 v169, v169
	v_add_f32_e32 v179, 1.0, v179
	v_add_f32_e32 v169, 1.0, v169
	v_rcp_f32_e32 v169, v169
	s_nop 0
	v_mul_f32_e32 v171, 0xbfb8aa3b, v183
	v_exp_f32_e32 v171, v171
	s_nop 0
	v_add_f32_e32 v171, 1.0, v171
	v_rcp_f32_e32 v171, v171
	s_nop 0
	v_mul_f32_e32 v173, 0xbfb8aa3b, v185
	v_exp_f32_e32 v173, v173
	s_nop 0
	v_add_f32_e32 v173, 1.0, v173
	v_rcp_f32_e32 v173, v173
	s_nop 0
	v_mul_f32_e32 v175, 0xbfb8aa3b, v180
	v_exp_f32_e32 v175, v175
	s_nop 0
	v_add_f32_e32 v175, 1.0, v175
	v_rcp_f32_e32 v175, v175
	s_nop 0
	v_rcp_f32_e32 v178, v178
	s_nop 0
	v_mul_f32_e32 v180, 0xbfb8aa3b, v181
	v_exp_f32_e32 v180, v180
	s_nop 0
	v_add_f32_e32 v180, 1.0, v180
	v_rcp_f32_e32 v181, v180
	s_nop 0
	s_mov_b64 s[2:3], 0x90000
	v_rcp_f32_e32 v179, v179
	s_nop 0
	v_cvt_pk_bf16_f32 v180, v0, v171
	v_cvt_pk_bf16_f32 v181, v175, v181
	v_cvt_pk_bf16_f32 v182, v169, v173
	v_cvt_pk_bf16_f32 v183, v178, v179
	v_lshl_add_u64 v[178:179], v[176:177], 0, s[2:3]
	s_mov_b32 s2, 0x90000
	v_add_co_u32_e32 v184, vcc, s2, v176
	s_nop 1
	v_addc_co_u32_e32 v185, vcc, 0, v177, vcc
	global_store_dwordx4 v[184:185], v[180:183], off
	v_pk_fma_f32 v[184:185], v[38:39], v[164:165], v[94:95] op_sel_hi:[1,0,1]
	s_nop 0
	v_mul_f32_e32 v0, 0xbfb8aa3b, v184
	v_exp_f32_e32 v0, v0
	v_pk_fma_f32 v[182:183], v[40:41], v[164:165], v[96:97] op_sel_hi:[1,0,1]
	v_pk_fma_f32 v[180:181], v[36:37], v[164:165], v[92:93] op_sel_hi:[1,0,1]
	v_add_f32_e32 v0, 1.0, v0
	v_mul_f32_e32 v180, 0xbfb8aa3b, v180
	v_exp_f32_e32 v180, v180
	v_rcp_f32_e32 v0, v0
	s_nop 0
	v_mul_f32_e32 v169, 0xbfb8aa3b, v186
	v_exp_f32_e32 v169, v169
	v_add_f32_e32 v180, 1.0, v180
	v_add_f32_e32 v169, 1.0, v169
	v_rcp_f32_e32 v169, v169
	s_nop 0
	v_mul_f32_e32 v171, 0xbfb8aa3b, v185
	v_exp_f32_e32 v171, v171
	s_nop 0
	v_add_f32_e32 v171, 1.0, v171
	v_rcp_f32_e32 v171, v171
	s_nop 0
	v_mul_f32_e32 v173, 0xbfb8aa3b, v187
	v_exp_f32_e32 v173, v173
	s_nop 0
	v_add_f32_e32 v173, 1.0, v173
	v_rcp_f32_e32 v173, v173
	s_nop 0
	v_mul_f32_e32 v175, 0xbfb8aa3b, v182
	v_exp_f32_e32 v175, v175
	s_nop 0
	v_add_f32_e32 v175, 1.0, v175
	v_rcp_f32_e32 v175, v175
	s_nop 0
	v_rcp_f32_e32 v184, v180
	s_nop 0
	v_mul_f32_e32 v180, 0xbfb8aa3b, v183
	v_exp_f32_e32 v180, v180
	s_nop 0
	v_add_f32_e32 v180, 1.0, v180
	v_rcp_f32_e32 v182, v180
	s_nop 0
	v_mul_f32_e32 v180, 0xbfb8aa3b, v181
	v_exp_f32_e32 v180, v180
	s_nop 0
	v_add_f32_e32 v180, 1.0, v180
	v_rcp_f32_e32 v183, v180
	s_nop 0
	v_cvt_pk_bf16_f32 v180, v0, v171
	v_cvt_pk_bf16_f32 v181, v175, v182
	v_cvt_pk_bf16_f32 v182, v169, v173
	v_cvt_pk_bf16_f32 v183, v184, v183
	global_store_dwordx4 v[178:179], v[180:183], off offset:256
	v_pk_fma_f32 v[184:185], v[26:27], v[162:163], v[106:107] op_sel_hi:[1,0,1]
	v_pk_fma_f32 v[178:179], v[28:29], v[162:163], v[108:109] op_sel_hi:[1,0,1]
	v_pk_fma_f32 v[182:183], v[30:31], v[162:163], v[110:111] op_sel_hi:[1,0,1]
	v_pk_fma_f32 v[180:181], v[32:33], v[162:163], v[112:113] op_sel_hi:[1,0,1]
	v_mul_f32_e32 v0, 0xbfb8aa3b, v182
	v_exp_f32_e32 v0, v0
	v_mul_f32_e32 v178, 0xbfb8aa3b, v178
	v_exp_f32_e32 v178, v178
	v_mul_f32_e32 v179, 0xbfb8aa3b, v179
	v_add_f32_e32 v0, 1.0, v0
	v_add_f32_e32 v178, 1.0, v178
	v_exp_f32_e32 v179, v179
	v_pk_fma_f32 v[186:187], v[18:19], v[162:163], v[90:91] op_sel_hi:[1,0,1]
	v_rcp_f32_e32 v0, v0
	s_nop 0
	v_mul_f32_e32 v169, 0xbfb8aa3b, v184
	v_exp_f32_e32 v169, v169
	v_add_f32_e32 v179, 1.0, v179
	v_add_f32_e32 v169, 1.0, v169
	v_rcp_f32_e32 v169, v169
	s_nop 0
	v_mul_f32_e32 v171, 0xbfb8aa3b, v183
	v_exp_f32_e32 v171, v171
	s_nop 0
	v_add_f32_e32 v171, 1.0, v171
	v_rcp_f32_e32 v171, v171
	s_nop 0
	v_mul_f32_e32 v173, 0xbfb8aa3b, v185
	v_exp_f32_e32 v173, v173
	s_nop 0
	v_add_f32_e32 v173, 1.0, v173
	v_rcp_f32_e32 v173, v173
	s_nop 0
	v_mul_f32_e32 v175, 0xbfb8aa3b, v180
	v_exp_f32_e32 v175, v175
	s_nop 0
	v_add_f32_e32 v175, 1.0, v175
	v_rcp_f32_e32 v175, v175
	s_nop 0
	v_rcp_f32_e32 v178, v178
	s_nop 0
	v_mul_f32_e32 v180, 0xbfb8aa3b, v181
	v_exp_f32_e32 v180, v180
	s_nop 0
	v_add_f32_e32 v180, 1.0, v180
	v_rcp_f32_e32 v181, v180
	s_nop 0
	s_mov_b64 s[2:3], 0xa0000
	v_rcp_f32_e32 v179, v179
	s_nop 0
	v_cvt_pk_bf16_f32 v180, v0, v171
; __device__ __forceinline__ float sigmoidf_(float x) { return 1.0f / (1.0f + __builtin_amdgcn_exp2f(-1.4426950408889634f * x)); }
; #define EPIIN_PACK(w, a, b) do { (w).x = cvt_pk_bf16((a)[0], (a)[1]); (w).y = cvt_pk_bf16((a)[2], (a)[3]); (w).z = cvt_pk_bf16((b)[0], (b)[1]); (w).w = cvt_pk_bf16((b)[2], (b)[3]); } while (0)
;     __device__ __forceinline__ void operator()(const f32x4 (&acc_)[2][2][4][2], const Unit& u, int wr, int wc, int fr, int fq) const {
;     ...
; #pragma unroll
;             for (int ai = 0; ai < 2; ++ai)
; #pragma unroll
;                 for (int m = 0; m < 4; ++m) { const size_t row = rowb + ai * HALF + m * 16;
; #pragma unroll
;                     for (int bj = 0; bj < 2; ++bj) { f32x4 a = EPIIN_VAL(ai, bj, m, 0), b = EPIIN_VAL(ai, bj, m, 1);
; #pragma unroll
;                         for (int i = 0; i < 4; ++i) { a[i] = sigmoidf_(a[i]); b[i] = sigmoidf_(b[i]); }
;                         u32x4 w; EPIIN_PACK(w, a, b);
;                         *(u32x4*)(GATES + row * 2048 + (pn - 8) * 256 + bj * HALF + wc * 32 + fq * 8) = w; } }
	v_cvt_pk_bf16_f32 v181, v175, v181
	v_cvt_pk_bf16_f32 v182, v169, v173
	v_cvt_pk_bf16_f32 v183, v178, v179
	v_lshl_add_u64 v[178:179], v[176:177], 0, s[2:3]
	s_mov_b32 s2, 0xa0000
	v_add_co_u32_e32 v184, vcc, s2, v176
	s_nop 1
	v_addc_co_u32_e32 v185, vcc, 0, v177, vcc
	global_store_dwordx4 v[184:185], v[180:183], off
	v_pk_fma_f32 v[184:185], v[22:23], v[162:163], v[94:95] op_sel_hi:[1,0,1]
	s_nop 0
	v_mul_f32_e32 v0, 0xbfb8aa3b, v184
	v_exp_f32_e32 v0, v0
	v_pk_fma_f32 v[182:183], v[24:25], v[162:163], v[96:97] op_sel_hi:[1,0,1]
	v_pk_fma_f32 v[180:181], v[20:21], v[162:163], v[92:93] op_sel_hi:[1,0,1]
	v_add_f32_e32 v0, 1.0, v0
	v_mul_f32_e32 v180, 0xbfb8aa3b, v180
	v_exp_f32_e32 v180, v180
	v_rcp_f32_e32 v0, v0
	s_nop 0
	v_mul_f32_e32 v169, 0xbfb8aa3b, v186
	v_exp_f32_e32 v169, v169
	v_add_f32_e32 v180, 1.0, v180
	v_add_f32_e32 v169, 1.0, v169
	v_rcp_f32_e32 v169, v169
	s_nop 0
	v_mul_f32_e32 v171, 0xbfb8aa3b, v185
	v_exp_f32_e32 v171, v171
	s_nop 0
	v_add_f32_e32 v171, 1.0, v171
	v_rcp_f32_e32 v171, v171
	s_nop 0
	v_mul_f32_e32 v173, 0xbfb8aa3b, v187
	v_exp_f32_e32 v173, v173
	s_nop 0
	v_add_f32_e32 v173, 1.0, v173
	v_rcp_f32_e32 v173, v173
	s_nop 0
	v_mul_f32_e32 v175, 0xbfb8aa3b, v182
	v_exp_f32_e32 v175, v175
	s_nop 0
	v_add_f32_e32 v175, 1.0, v175
	v_rcp_f32_e32 v175, v175
	s_nop 0
	v_rcp_f32_e32 v184, v180
	s_nop 0
	v_mul_f32_e32 v180, 0xbfb8aa3b, v183
	v_exp_f32_e32 v180, v180
	s_nop 0
	v_add_f32_e32 v180, 1.0, v180
	v_rcp_f32_e32 v182, v180
	s_nop 0
	v_mul_f32_e32 v180, 0xbfb8aa3b, v181
	v_exp_f32_e32 v180, v180
	s_nop 0
	v_add_f32_e32 v180, 1.0, v180
	v_rcp_f32_e32 v183, v180
	s_nop 0
	v_cvt_pk_bf16_f32 v180, v0, v171
	v_cvt_pk_bf16_f32 v181, v175, v182
	v_cvt_pk_bf16_f32 v182, v169, v173
	v_cvt_pk_bf16_f32 v183, v184, v183
	global_store_dwordx4 v[178:179], v[180:183], off offset:256
	v_pk_fma_f32 v[184:185], v[10:11], v[160:161], v[106:107] op_sel_hi:[1,0,1]
	v_pk_fma_f32 v[178:179], v[12:13], v[160:161], v[108:109] op_sel_hi:[1,0,1]
	v_pk_fma_f32 v[182:183], v[14:15], v[160:161], v[110:111] op_sel_hi:[1,0,1]
	v_pk_fma_f32 v[180:181], v[16:17], v[160:161], v[112:113] op_sel_hi:[1,0,1]
	v_mul_f32_e32 v0, 0xbfb8aa3b, v182
	v_exp_f32_e32 v0, v0
	v_mul_f32_e32 v178, 0xbfb8aa3b, v178
	v_exp_f32_e32 v178, v178
	v_mul_f32_e32 v179, 0xbfb8aa3b, v179
	v_add_f32_e32 v0, 1.0, v0
	v_add_f32_e32 v178, 1.0, v178
	v_exp_f32_e32 v179, v179
	v_rcp_f32_e32 v0, v0
	s_nop 0
	v_mul_f32_e32 v169, 0xbfb8aa3b, v184
	v_exp_f32_e32 v169, v169
	v_add_f32_e32 v179, 1.0, v179
	v_add_f32_e32 v169, 1.0, v169
	v_rcp_f32_e32 v169, v169
	s_nop 0
	v_mul_f32_e32 v171, 0xbfb8aa3b, v183
	v_exp_f32_e32 v171, v171
	s_nop 0
	v_add_f32_e32 v171, 1.0, v171
	v_rcp_f32_e32 v171, v171
	s_nop 0
	v_mul_f32_e32 v173, 0xbfb8aa3b, v185
	v_exp_f32_e32 v173, v173
	s_nop 0
	v_add_f32_e32 v173, 1.0, v173
	v_rcp_f32_e32 v173, v173
	s_nop 0
	v_mul_f32_e32 v175, 0xbfb8aa3b, v180
	v_exp_f32_e32 v175, v175
	s_nop 0
	v_add_f32_e32 v175, 1.0, v175
	v_rcp_f32_e32 v175, v175
	s_nop 0
	v_rcp_f32_e32 v178, v178
	s_nop 0
	v_mul_f32_e32 v180, 0xbfb8aa3b, v181
	v_exp_f32_e32 v180, v180
	s_nop 0
	v_add_f32_e32 v180, 1.0, v180
	v_rcp_f32_e32 v181, v180
	s_nop 0
	s_mov_b64 s[2:3], 0xb0000
	v_rcp_f32_e32 v179, v179
	s_nop 0
	v_cvt_pk_bf16_f32 v180, v0, v171
	v_cvt_pk_bf16_f32 v181, v175, v181
	v_cvt_pk_bf16_f32 v182, v169, v173
	v_cvt_pk_bf16_f32 v183, v178, v179
	v_lshl_add_u64 v[178:179], v[176:177], 0, s[2:3]
	s_mov_b32 s2, 0xb0000
	v_add_co_u32_e32 v176, vcc, s2, v176
	v_pk_fma_f32 v[184:185], v[2:3], v[160:161], v[90:91] op_sel_hi:[1,0,1]
	s_nop 0
	v_addc_co_u32_e32 v177, vcc, 0, v177, vcc
	global_store_dwordx4 v[176:177], v[180:183], off
	v_pk_fma_f32 v[176:177], v[4:5], v[160:161], v[92:93] op_sel_hi:[1,0,1]
	s_nop 0
	v_pk_fma_f32 v[182:183], v[6:7], v[160:161], v[94:95] op_sel_hi:[1,0,1]
	v_pk_fma_f32 v[180:181], v[8:9], v[160:161], v[96:97] op_sel_hi:[1,0,1]
	v_mul_f32_e32 v0, 0xbfb8aa3b, v182
	v_exp_f32_e32 v0, v0
	v_mul_f32_e32 v176, 0xbfb8aa3b, v176
	v_exp_f32_e32 v176, v176
	v_mul_f32_e32 v177, 0xbfb8aa3b, v177
	v_add_f32_e32 v0, 1.0, v0
	v_add_f32_e32 v176, 1.0, v176
	v_exp_f32_e32 v177, v177
	v_rcp_f32_e32 v0, v0
	s_nop 0
	v_mul_f32_e32 v169, 0xbfb8aa3b, v184
	v_exp_f32_e32 v169, v169
	v_add_f32_e32 v177, 1.0, v177
	v_add_f32_e32 v169, 1.0, v169
	v_rcp_f32_e32 v169, v169
	s_nop 0
	v_mul_f32_e32 v171, 0xbfb8aa3b, v183
	v_exp_f32_e32 v171, v171
	s_nop 0
	v_add_f32_e32 v171, 1.0, v171
	v_rcp_f32_e32 v171, v171
	s_nop 0
	v_mul_f32_e32 v173, 0xbfb8aa3b, v185
	v_exp_f32_e32 v173, v173
	s_nop 0
	v_add_f32_e32 v173, 1.0, v173
	v_rcp_f32_e32 v173, v173
	s_nop 0
	v_mul_f32_e32 v175, 0xbfb8aa3b, v180
	v_exp_f32_e32 v175, v175
	s_nop 0
	v_add_f32_e32 v175, 1.0, v175
	v_rcp_f32_e32 v175, v175
	s_nop 0
	v_rcp_f32_e32 v176, v176
	s_nop 0
	v_mul_f32_e32 v180, 0xbfb8aa3b, v181
	v_exp_f32_e32 v180, v180
	s_nop 0
	v_add_f32_e32 v180, 1.0, v180
	v_rcp_f32_e32 v181, v180
	s_nop 0
	s_mov_b64 s[2:3], 0
	v_rcp_f32_e32 v177, v177
	s_nop 0
	v_cvt_pk_bf16_f32 v180, v0, v171
	v_cvt_pk_bf16_f32 v181, v175, v181
	v_cvt_pk_bf16_f32 v182, v169, v173
	v_cvt_pk_bf16_f32 v183, v176, v177
	global_store_dwordx4 v[178:179], v[180:183], off offset:256
